# v26 plus nt hint on the bf16 residual-copy stores of the down/out projection epilogues
# baseline (speedup 1.0000x reference)
.LBB0_294:
	ds_read_b128 v[130:133], v207
	ds_read_b128 v[134:137], v207 offset:1024
	ds_read_b128 v[138:141], v207 offset:2048
	ds_read_b128 v[142:145], v207 offset:3072
	ds_read_b128 v[146:149], v208
	ds_read_b128 v[150:153], v208 offset:1024
	ds_read_b128 v[154:157], v208 offset:2048
	ds_read_b128 v[158:161], v208 offset:3072
	s_add_u32 s20, s18, 0xfff50080
	s_addc_u32 s21, s19, -1
	s_cmp_eq_u32 s51, 40
	s_cselect_b32 s23, s9, s21
	s_cselect_b32 s22, s8, s20
	s_cselect_b32 s21, s11, s50
	s_cselect_b32 s20, s10, s49
	v_lshl_add_u64 v[218:219], s[18:19], 0, v[186:187]
	s_add_i32 m0, s31, 0xc000
	ds_read_b128 v[162:165], v209
	ds_read_b128 v[166:169], v209 offset:1024
	ds_read_b128 v[170:173], v209 offset:2048
	ds_read_b128 v[174:177], v209 offset:3072
	ds_read_b128 v[194:197], v209 offset:4096
	ds_read_b128 v[198:201], v209 offset:5120
	ds_read_b128 v[202:205], v209 offset:6144
	ds_read_b128 v[214:217], v209 offset:7168
	global_load_lds_dwordx4 v[218:219], off
	v_lshl_add_u64 v[218:219], s[18:19], 0, v[188:189]
	s_add_i32 m0, s31, 0xe000
	s_nop 0
	global_load_lds_dwordx4 v[218:219], off
	s_waitcnt vmcnt(8)
	s_waitcnt lgkmcnt(0)
	s_barrier
	s_setprio 1
	s_waitcnt lgkmcnt(0)
	v_mfma_f32_16x16x32_bf16 v[126:129], v[130:133], v[162:165], v[126:129]
	v_mfma_f32_16x16x32_bf16 v[122:125], v[138:141], v[162:165], v[122:125]
	v_mfma_f32_16x16x32_bf16 v[110:113], v[130:133], v[170:173], v[110:113]
	v_mfma_f32_16x16x32_bf16 v[106:109], v[138:141], v[170:173], v[106:109]
	v_mfma_f32_16x16x32_bf16 v[94:97], v[130:133], v[194:197], v[94:97]
	v_mfma_f32_16x16x32_bf16 v[90:93], v[138:141], v[194:197], v[90:93]
	v_mfma_f32_16x16x32_bf16 v[78:81], v[130:133], v[202:205], v[78:81]
	v_mfma_f32_16x16x32_bf16 v[74:77], v[138:141], v[202:205], v[74:77]
	v_mfma_f32_16x16x32_bf16 v[126:129], v[134:137], v[166:169], v[126:129]
	v_mfma_f32_16x16x32_bf16 v[122:125], v[142:145], v[166:169], v[122:125]
	v_mfma_f32_16x16x32_bf16 v[110:113], v[134:137], v[174:177], v[110:113]
	v_mfma_f32_16x16x32_bf16 v[106:109], v[142:145], v[174:177], v[106:109]
	v_mfma_f32_16x16x32_bf16 v[94:97], v[134:137], v[198:201], v[94:97]
	v_mfma_f32_16x16x32_bf16 v[90:93], v[142:145], v[198:201], v[90:93]
	v_mfma_f32_16x16x32_bf16 v[78:81], v[134:137], v[214:217], v[78:81]
	v_mfma_f32_16x16x32_bf16 v[74:77], v[142:145], v[214:217], v[74:77]
	s_setprio 0
	s_setprio 1
	v_mfma_f32_16x16x32_bf16 v[118:121], v[146:149], v[162:165], v[118:121]
	v_mfma_f32_16x16x32_bf16 v[114:117], v[154:157], v[162:165], v[114:117]
	v_mfma_f32_16x16x32_bf16 v[102:105], v[146:149], v[170:173], v[102:105]
	v_mfma_f32_16x16x32_bf16 v[98:101], v[154:157], v[170:173], v[98:101]
	v_mfma_f32_16x16x32_bf16 v[86:89], v[146:149], v[194:197], v[86:89]
	v_mfma_f32_16x16x32_bf16 v[82:85], v[154:157], v[194:197], v[82:85]
	v_mfma_f32_16x16x32_bf16 v[70:73], v[146:149], v[202:205], v[70:73]
	v_mfma_f32_16x16x32_bf16 v[66:69], v[154:157], v[202:205], v[66:69]
	v_mfma_f32_16x16x32_bf16 v[118:121], v[150:153], v[166:169], v[118:121]
	v_mfma_f32_16x16x32_bf16 v[114:117], v[158:161], v[166:169], v[114:117]
	v_mfma_f32_16x16x32_bf16 v[102:105], v[150:153], v[174:177], v[102:105]
	v_mfma_f32_16x16x32_bf16 v[98:101], v[158:161], v[174:177], v[98:101]
	v_mfma_f32_16x16x32_bf16 v[86:89], v[150:153], v[198:201], v[86:89]
	v_mfma_f32_16x16x32_bf16 v[82:85], v[158:161], v[198:201], v[82:85]
	v_mfma_f32_16x16x32_bf16 v[70:73], v[150:153], v[214:217], v[70:73]
	v_mfma_f32_16x16x32_bf16 v[66:69], v[158:161], v[214:217], v[66:69]
	s_setprio 0
	s_barrier
	s_add_i32 s52, s41, s30
	v_lshl_add_u64 v[218:219], s[20:21], 0, v[180:181]
	s_mov_b32 m0, s52
	ds_read_b128 v[162:165], v209 offset:16384
	ds_read_b128 v[166:169], v209 offset:17408
	ds_read_b128 v[170:173], v209 offset:18432
	ds_read_b128 v[174:177], v209 offset:19456
	ds_read_b128 v[194:197], v209 offset:20480
	ds_read_b128 v[198:201], v209 offset:21504
	ds_read_b128 v[202:205], v209 offset:22528
	ds_read_b128 v[214:217], v209 offset:23552
	global_load_lds_dwordx4 v[218:219], off
	s_add_i32 m0, s52, 0x2000
	s_add_u32 s52, s20, 0xb0000
	v_lshl_add_u64 v[220:221], s[20:21], 0, v[184:185]
	s_addc_u32 s53, s21, 0
	s_add_i32 s54, s42, s30
	global_load_lds_dwordx4 v[220:221], off
	v_lshl_add_u64 v[222:223], s[52:53], 0, v[180:181]
	s_mov_b32 m0, s54
	v_lshl_add_u64 v[224:225], s[22:23], 0, v[182:183]
	global_load_lds_dwordx4 v[222:223], off
	v_lshl_add_u64 v[222:223], s[52:53], 0, v[184:185]
	s_add_i32 m0, s54, 0x2000
	s_nop 0
	global_load_lds_dwordx4 v[222:223], off
	v_lshl_add_u64 v[222:223], s[22:23], 0, v[178:179]
	s_mov_b32 m0, s31
	s_nop 0
	global_load_lds_dwordx4 v[222:223], off
	s_mov_b32 m0, s33
	s_nop 0
	global_load_lds_dwordx4 v[224:225], off
	s_waitcnt vmcnt(8)
	s_waitcnt lgkmcnt(0)
	s_barrier
	s_setprio 1
	s_waitcnt lgkmcnt(0)
	v_mfma_f32_16x16x32_bf16 v[62:65], v[130:133], v[162:165], v[62:65]
	v_mfma_f32_16x16x32_bf16 v[58:61], v[138:141], v[162:165], v[58:61]
	v_mfma_f32_16x16x32_bf16 v[46:49], v[130:133], v[170:173], v[46:49]
	v_mfma_f32_16x16x32_bf16 v[42:45], v[138:141], v[170:173], v[42:45]
	v_mfma_f32_16x16x32_bf16 v[30:33], v[130:133], v[194:197], v[30:33]
	v_mfma_f32_16x16x32_bf16 v[26:29], v[138:141], v[194:197], v[26:29]
	v_mfma_f32_16x16x32_bf16 v[14:17], v[130:133], v[202:205], v[14:17]
	v_mfma_f32_16x16x32_bf16 v[10:13], v[138:141], v[202:205], v[10:13]
	v_mfma_f32_16x16x32_bf16 v[62:65], v[134:137], v[166:169], v[62:65]
	v_mfma_f32_16x16x32_bf16 v[58:61], v[142:145], v[166:169], v[58:61]
	v_mfma_f32_16x16x32_bf16 v[46:49], v[134:137], v[174:177], v[46:49]
	v_mfma_f32_16x16x32_bf16 v[42:45], v[142:145], v[174:177], v[42:45]
	v_mfma_f32_16x16x32_bf16 v[30:33], v[134:137], v[198:201], v[30:33]
	v_mfma_f32_16x16x32_bf16 v[26:29], v[142:145], v[198:201], v[26:29]
	v_mfma_f32_16x16x32_bf16 v[14:17], v[134:137], v[214:217], v[14:17]
	v_mfma_f32_16x16x32_bf16 v[10:13], v[142:145], v[214:217], v[10:13]
	s_setprio 0
	s_setprio 1
	v_mfma_f32_16x16x32_bf16 v[54:57], v[146:149], v[162:165], v[54:57]
	v_mfma_f32_16x16x32_bf16 v[50:53], v[154:157], v[162:165], v[50:53]
	v_mfma_f32_16x16x32_bf16 v[38:41], v[146:149], v[170:173], v[38:41]
	v_mfma_f32_16x16x32_bf16 v[34:37], v[154:157], v[170:173], v[34:37]
	v_mfma_f32_16x16x32_bf16 v[22:25], v[146:149], v[194:197], v[22:25]
	v_mfma_f32_16x16x32_bf16 v[18:21], v[154:157], v[194:197], v[18:21]
	v_mfma_f32_16x16x32_bf16 v[6:9], v[146:149], v[202:205], v[6:9]
	v_mfma_f32_16x16x32_bf16 v[2:5], v[154:157], v[202:205], v[2:5]
	v_mfma_f32_16x16x32_bf16 v[54:57], v[150:153], v[166:169], v[54:57]
	v_mfma_f32_16x16x32_bf16 v[50:53], v[158:161], v[166:169], v[50:53]
	v_mfma_f32_16x16x32_bf16 v[38:41], v[150:153], v[174:177], v[38:41]
	v_mfma_f32_16x16x32_bf16 v[34:37], v[158:161], v[174:177], v[34:37]
	v_mfma_f32_16x16x32_bf16 v[22:25], v[150:153], v[198:201], v[22:25]
	v_mfma_f32_16x16x32_bf16 v[18:21], v[158:161], v[198:201], v[18:21]
	v_mfma_f32_16x16x32_bf16 v[6:9], v[150:153], v[214:217], v[6:9]
	v_mfma_f32_16x16x32_bf16 v[2:5], v[158:161], v[214:217], v[2:5]
	s_setprio 0
	s_barrier
	ds_read_b128 v[130:133], v211
	ds_read_b128 v[134:137], v211 offset:1024
	ds_read_b128 v[138:141], v211 offset:2048
	ds_read_b128 v[142:145], v211 offset:3072
	ds_read_b128 v[146:149], v212
	ds_read_b128 v[150:153], v212 offset:1024
	ds_read_b128 v[154:157], v212 offset:2048
	ds_read_b128 v[158:161], v212 offset:3072
	s_add_u32 s22, s22, 0xb0000
	s_addc_u32 s23, s23, 0
	s_mov_b32 m0, s34
	v_lshl_add_u64 v[226:227], s[22:23], 0, v[178:179]
	ds_read_b128 v[162:165], v209 offset:32768
	ds_read_b128 v[166:169], v209 offset:33792
	ds_read_b128 v[170:173], v209 offset:34816
	ds_read_b128 v[174:177], v209 offset:35840
	ds_read_b128 v[194:197], v209 offset:36864
	ds_read_b128 v[198:201], v209 offset:37888
	ds_read_b128 v[202:205], v209 offset:38912
	ds_read_b128 v[214:217], v209 offset:39936
	global_load_lds_dwordx4 v[226:227], off
	v_lshl_add_u64 v[226:227], s[22:23], 0, v[182:183]
	s_mov_b32 m0, s35
	s_nop 0
	global_load_lds_dwordx4 v[226:227], off
	s_waitcnt vmcnt(8)
	s_waitcnt lgkmcnt(0)
	s_barrier
	s_setprio 1
	s_waitcnt lgkmcnt(0)
	v_mfma_f32_16x16x32_bf16 v[126:129], v[130:133], v[162:165], v[126:129]
	v_mfma_f32_16x16x32_bf16 v[122:125], v[138:141], v[162:165], v[122:125]
	v_mfma_f32_16x16x32_bf16 v[110:113], v[130:133], v[170:173], v[110:113]
	v_mfma_f32_16x16x32_bf16 v[106:109], v[138:141], v[170:173], v[106:109]
	v_mfma_f32_16x16x32_bf16 v[94:97], v[130:133], v[194:197], v[94:97]
	v_mfma_f32_16x16x32_bf16 v[90:93], v[138:141], v[194:197], v[90:93]
	v_mfma_f32_16x16x32_bf16 v[78:81], v[130:133], v[202:205], v[78:81]
	v_mfma_f32_16x16x32_bf16 v[74:77], v[138:141], v[202:205], v[74:77]
	v_mfma_f32_16x16x32_bf16 v[126:129], v[134:137], v[166:169], v[126:129]
	v_mfma_f32_16x16x32_bf16 v[122:125], v[142:145], v[166:169], v[122:125]
	v_mfma_f32_16x16x32_bf16 v[110:113], v[134:137], v[174:177], v[110:113]
	v_mfma_f32_16x16x32_bf16 v[106:109], v[142:145], v[174:177], v[106:109]
	v_mfma_f32_16x16x32_bf16 v[94:97], v[134:137], v[198:201], v[94:97]
	v_mfma_f32_16x16x32_bf16 v[90:93], v[142:145], v[198:201], v[90:93]
	v_mfma_f32_16x16x32_bf16 v[78:81], v[134:137], v[214:217], v[78:81]
	v_mfma_f32_16x16x32_bf16 v[74:77], v[142:145], v[214:217], v[74:77]
	s_setprio 0
	s_setprio 1
	v_mfma_f32_16x16x32_bf16 v[118:121], v[146:149], v[162:165], v[118:121]
	v_mfma_f32_16x16x32_bf16 v[114:117], v[154:157], v[162:165], v[114:117]
	v_mfma_f32_16x16x32_bf16 v[102:105], v[146:149], v[170:173], v[102:105]
	v_mfma_f32_16x16x32_bf16 v[98:101], v[154:157], v[170:173], v[98:101]
	v_mfma_f32_16x16x32_bf16 v[86:89], v[146:149], v[194:197], v[86:89]
	v_mfma_f32_16x16x32_bf16 v[82:85], v[154:157], v[194:197], v[82:85]
	v_mfma_f32_16x16x32_bf16 v[70:73], v[146:149], v[202:205], v[70:73]
	v_mfma_f32_16x16x32_bf16 v[66:69], v[154:157], v[202:205], v[66:69]
	v_mfma_f32_16x16x32_bf16 v[118:121], v[150:153], v[166:169], v[118:121]
	v_mfma_f32_16x16x32_bf16 v[114:117], v[158:161], v[166:169], v[114:117]
	v_mfma_f32_16x16x32_bf16 v[102:105], v[150:153], v[174:177], v[102:105]
	v_mfma_f32_16x16x32_bf16 v[98:101], v[158:161], v[174:177], v[98:101]
	v_mfma_f32_16x16x32_bf16 v[86:89], v[150:153], v[198:201], v[86:89]
	v_mfma_f32_16x16x32_bf16 v[82:85], v[158:161], v[198:201], v[82:85]
	v_mfma_f32_16x16x32_bf16 v[70:73], v[150:153], v[214:217], v[70:73]
	v_mfma_f32_16x16x32_bf16 v[66:69], v[158:161], v[214:217], v[66:69]
	s_setprio 0
	s_barrier
	s_add_i32 s22, s43, s30
	v_lshl_add_u64 v[218:219], v[218:219], 0, s[14:15]
	s_mov_b32 m0, s22
	ds_read_b128 v[162:165], v209 offset:49152
	ds_read_b128 v[166:169], v209 offset:50176
	ds_read_b128 v[170:173], v209 offset:51200
	ds_read_b128 v[174:177], v209 offset:52224
	ds_read_b128 v[194:197], v209 offset:53248
	ds_read_b128 v[198:201], v209 offset:54272
	ds_read_b128 v[202:205], v209 offset:55296
	ds_read_b128 v[214:217], v209 offset:56320
	global_load_lds_dwordx4 v[218:219], off
	s_add_i32 m0, s22, 0x2000
	s_add_u32 s20, s20, 0xb0080
	v_lshl_add_u64 v[218:219], v[220:221], 0, s[14:15]
	s_addc_u32 s21, s21, 0
	s_add_i32 s22, s44, s30
	global_load_lds_dwordx4 v[218:219], off
	v_lshl_add_u64 v[218:219], s[20:21], 0, v[180:181]
	s_mov_b32 m0, s22
	s_nop 0
	global_load_lds_dwordx4 v[218:219], off
	v_lshl_add_u64 v[218:219], s[20:21], 0, v[184:185]
	s_add_i32 m0, s22, 0x2000
	s_nop 0
	global_load_lds_dwordx4 v[218:219], off
	v_lshl_add_u64 v[218:219], v[222:223], 0, s[14:15]
	s_mov_b32 m0, s37
	s_nop 0
	global_load_lds_dwordx4 v[218:219], off
	v_lshl_add_u64 v[218:219], v[224:225], 0, s[14:15]
	s_mov_b32 m0, s38
	s_nop 0
	global_load_lds_dwordx4 v[218:219], off
	s_waitcnt vmcnt(8)
	s_waitcnt lgkmcnt(0)
	s_barrier
	s_setprio 1
	s_waitcnt lgkmcnt(0)
	v_mfma_f32_16x16x32_bf16 v[62:65], v[130:133], v[162:165], v[62:65]
	v_mfma_f32_16x16x32_bf16 v[58:61], v[138:141], v[162:165], v[58:61]
	v_mfma_f32_16x16x32_bf16 v[46:49], v[130:133], v[170:173], v[46:49]
	v_mfma_f32_16x16x32_bf16 v[42:45], v[138:141], v[170:173], v[42:45]
	v_mfma_f32_16x16x32_bf16 v[30:33], v[130:133], v[194:197], v[30:33]
	v_mfma_f32_16x16x32_bf16 v[26:29], v[138:141], v[194:197], v[26:29]
	v_mfma_f32_16x16x32_bf16 v[14:17], v[130:133], v[202:205], v[14:17]
	v_mfma_f32_16x16x32_bf16 v[10:13], v[138:141], v[202:205], v[10:13]
	v_mfma_f32_16x16x32_bf16 v[62:65], v[134:137], v[166:169], v[62:65]
	v_mfma_f32_16x16x32_bf16 v[58:61], v[142:145], v[166:169], v[58:61]
	v_mfma_f32_16x16x32_bf16 v[46:49], v[134:137], v[174:177], v[46:49]
	v_mfma_f32_16x16x32_bf16 v[42:45], v[142:145], v[174:177], v[42:45]
	v_mfma_f32_16x16x32_bf16 v[30:33], v[134:137], v[198:201], v[30:33]
	v_mfma_f32_16x16x32_bf16 v[26:29], v[142:145], v[198:201], v[26:29]
	v_mfma_f32_16x16x32_bf16 v[14:17], v[134:137], v[214:217], v[14:17]
	v_mfma_f32_16x16x32_bf16 v[10:13], v[142:145], v[214:217], v[10:13]
	s_setprio 0
	s_setprio 1
	v_mfma_f32_16x16x32_bf16 v[54:57], v[146:149], v[162:165], v[54:57]
	v_mfma_f32_16x16x32_bf16 v[50:53], v[154:157], v[162:165], v[50:53]
	v_mfma_f32_16x16x32_bf16 v[38:41], v[146:149], v[170:173], v[38:41]
	v_mfma_f32_16x16x32_bf16 v[34:37], v[154:157], v[170:173], v[34:37]
	v_mfma_f32_16x16x32_bf16 v[22:25], v[146:149], v[194:197], v[22:25]
	v_mfma_f32_16x16x32_bf16 v[18:21], v[154:157], v[194:197], v[18:21]
	v_mfma_f32_16x16x32_bf16 v[6:9], v[146:149], v[202:205], v[6:9]
	v_mfma_f32_16x16x32_bf16 v[2:5], v[154:157], v[202:205], v[2:5]
	v_mfma_f32_16x16x32_bf16 v[54:57], v[150:153], v[166:169], v[54:57]
	v_mfma_f32_16x16x32_bf16 v[50:53], v[158:161], v[166:169], v[50:53]
	v_mfma_f32_16x16x32_bf16 v[38:41], v[150:153], v[174:177], v[38:41]
	v_mfma_f32_16x16x32_bf16 v[34:37], v[158:161], v[174:177], v[34:37]
	v_mfma_f32_16x16x32_bf16 v[22:25], v[150:153], v[198:201], v[22:25]
	v_mfma_f32_16x16x32_bf16 v[18:21], v[158:161], v[198:201], v[18:21]
	v_mfma_f32_16x16x32_bf16 v[6:9], v[150:153], v[214:217], v[6:9]
	v_mfma_f32_16x16x32_bf16 v[2:5], v[158:161], v[214:217], v[2:5]
	s_setprio 0
	s_barrier
	s_add_i32 s51, s51, 2
	s_add_u32 s18, s18, 0x100
	s_addc_u32 s19, s19, 0
	s_add_u32 s49, s49, 0x100
	s_addc_u32 s50, s50, 0
	s_cmp_gt_u32 s51, 41
	s_cbranch_scc0 .LBB0_294
	s_load_dwordx16 s[80:95], s[76:77], 0x0
	v_lshl_add_u32 v198, s48, 8, v1
	v_lshl_or_b32 v194, s16, 8, v206
	v_ashrrev_i32_e32 v195, 31, v194
	v_ashrrev_i32_e32 v199, 31, v198
	s_waitcnt lgkmcnt(0)
	v_lshl_add_u64 v[196:197], v[194:195], 2, s[80:81]
	v_lshlrev_b64 v[130:131], 12, v[198:199]
	v_lshl_add_u64 v[130:131], v[196:197], 0, v[130:131]
	global_load_dwordx4 v[214:217], v[130:131], off nt
	global_load_dwordx4 v[218:221], v[130:131], off offset:16 nt
	global_load_dwordx4 v[222:225], v[130:131], off offset:512 nt
	global_load_dwordx4 v[226:229], v[130:131], off offset:528 nt
	v_or_b32_e32 v204, 16, v198
	v_or_b32_e32 v202, 32, v198
	v_or_b32_e32 v200, 48, v198
	v_ashrrev_i32_e32 v205, 31, v204
	v_ashrrev_i32_e32 v203, 31, v202
	v_ashrrev_i32_e32 v201, 31, v200
	v_lshlrev_b64 v[130:131], 12, v[204:205]
	v_lshlrev_b64 v[132:133], 12, v[202:203]
	v_lshlrev_b64 v[134:135], 12, v[200:201]
	v_lshl_add_u64 v[130:131], v[196:197], 0, v[130:131]
	v_lshl_add_u64 v[132:133], v[196:197], 0, v[132:133]
	v_lshl_add_u64 v[134:135], v[196:197], 0, v[134:135]
	global_load_dwordx4 v[170:173], v[130:131], off offset:16 nt
	global_load_dwordx4 v[174:177], v[130:131], off nt
	global_load_dwordx4 v[162:165], v[130:131], off offset:528 nt
	global_load_dwordx4 v[166:169], v[130:131], off offset:512 nt
	global_load_dwordx4 v[154:157], v[132:133], off offset:16 nt
	global_load_dwordx4 v[158:161], v[132:133], off nt
	global_load_dwordx4 v[146:149], v[132:133], off offset:528 nt
	global_load_dwordx4 v[150:153], v[132:133], off offset:512 nt
	global_load_dwordx4 v[138:141], v[134:135], off offset:16 nt
	global_load_dwordx4 v[142:145], v[134:135], off nt
	s_nop 0
	global_load_dwordx4 v[130:133], v[134:135], off offset:528 nt
	s_nop 0
	global_load_dwordx4 v[134:137], v[134:135], off offset:512 nt
	v_and_b32_e32 v230, 64, v210
	v_xor_b32_e32 v213, 16, v210
	v_add_u32_e32 v233, 64, v230
	v_xor_b32_e32 v232, 32, v210
	v_lshlrev_b64 v[230:231], 10, v[198:199]
	v_cmp_lt_i32_e32 vcc, v213, v233
	v_lshl_add_u64 v[230:231], v[230:231], 0, v[194:195]
	s_lshl_b32 s18, s16, 2
	v_cndmask_b32_e32 v213, v210, v213, vcc
	v_cmp_lt_i32_e32 vcc, v232, v233
	v_lshlrev_b32_e32 v213, 2, v213
	s_ashr_i32 s19, s18, 31
	v_cndmask_b32_e32 v236, v210, v232, vcc
	v_lshl_add_u64 v[232:233], v[230:231], 2, s[62:63]
	v_lshlrev_b64 v[230:231], 1, v[230:231]
	v_lshl_add_u64 v[234:235], s[2:3], 0, v[230:231]
	v_or_b32_e32 v230, 0x100, v230
	s_waitcnt vmcnt(0)
	v_pk_fma_f32 v[128:129], v[128:129], 0.5, v[216:217] op_sel_hi:[1,0,1]
	v_pk_fma_f32 v[126:127], v[126:127], 0.5, v[214:215] op_sel_hi:[1,0,1]
	v_pk_fma_f32 v[120:121], v[120:121], 0.5, v[224:225] op_sel_hi:[1,0,1]
	v_pk_fma_f32 v[118:119], v[118:119], 0.5, v[222:223] op_sel_hi:[1,0,1]
	v_pk_fma_f32 v[124:125], v[124:125], 0.5, v[220:221] op_sel_hi:[1,0,1]
	v_pk_fma_f32 v[122:123], v[122:123], 0.5, v[218:219] op_sel_hi:[1,0,1]
	v_pk_fma_f32 v[114:115], v[114:115], 0.5, v[226:227] op_sel_hi:[1,0,1]
	global_store_dwordx4 v[232:233], v[126:129], off nt
	global_store_dwordx4 v[232:233], v[122:125], off offset:16 nt
	v_cvt_pk_bf16_f32 v214, v126, v127
	v_cvt_pk_bf16_f32 v215, v128, v129
	v_mul_f32_e32 v218, v119, v119
	v_mul_f32_e32 v127, v127, v127
	v_mul_f32_e32 v129, v129, v129
	v_mul_f32_e32 v219, v121, v121
	v_pk_fma_f32 v[116:117], v[116:117], 0.5, v[228:229] op_sel_hi:[1,0,1]
	v_cvt_pk_bf16_f32 v216, v122, v123
	v_cvt_pk_bf16_f32 v217, v124, v125
	v_mul_f32_e32 v123, v123, v123
	v_mul_f32_e32 v125, v125, v125
	v_mul_f32_e32 v220, v115, v115
	v_fmac_f32_e32 v127, v126, v126
	v_fmac_f32_e32 v129, v128, v128
	v_fmac_f32_e32 v218, v118, v118
	v_fmac_f32_e32 v219, v120, v120
	v_mul_f32_e32 v221, v117, v117
	v_fmac_f32_e32 v123, v122, v122
	v_fmac_f32_e32 v125, v124, v124
	v_fmac_f32_e32 v220, v114, v114
	v_add_f32_e32 v122, v127, v129
	v_add_f32_e32 v124, v218, v219
	v_fmac_f32_e32 v221, v116, v116
	v_add_f32_e32 v122, v122, v123
	v_add_f32_e32 v123, v124, v220
	v_add_f32_e32 v122, v125, v122
	v_add_f32_e32 v123, v221, v123
	v_add_f32_e32 v122, v122, v123
	ds_bpermute_b32 v123, v213, v122
	global_store_dwordx4 v[234:235], v[214:217], off nt
	global_store_dwordx4 v[232:233], v[118:121], off offset:512 nt
	global_store_dwordx4 v[232:233], v[114:117], off offset:528 nt
	s_nop 0
	v_cvt_pk_bf16_f32 v118, v118, v119
	v_cvt_pk_bf16_f32 v119, v120, v121
	v_cvt_pk_bf16_f32 v120, v114, v115
	v_cvt_pk_bf16_f32 v121, v116, v117
	s_waitcnt lgkmcnt(0)
	v_add_f32_e32 v114, v122, v123
	v_lshlrev_b32_e32 v122, 2, v236
	ds_bpermute_b32 v115, v122, v114
	v_lshl_add_u64 v[116:117], s[2:3], 0, v[230:231]
	global_store_dwordx4 v[116:117], v[118:121], off nt
	s_and_saveexec_b64 s[20:21], s[4:5]
	s_cbranch_execz .LBB0_297
	s_waitcnt lgkmcnt(0)
	v_add_f32_e32 v116, v114, v115
	v_lshlrev_b64 v[114:115], 6, v[198:199]
	v_lshl_add_u64 v[114:115], s[12:13], 0, v[114:115]
	v_lshl_add_u64 v[114:115], s[18:19], 2, v[114:115]
	s_lshl_b32 s16, s36, 2
	v_lshl_add_u64 v[114:115], v[114:115], 0, s[16:17]
	global_store_dword v[114:115], v116, off
.LBB0_297:
	s_or_b64 exec, exec, s[20:21]
	s_waitcnt lgkmcnt(0)
	v_lshlrev_b64 v[114:115], 10, v[204:205]
	v_lshl_add_u64 v[118:119], v[114:115], 0, v[194:195]
	v_pk_fma_f32 v[112:113], v[112:113], 0.5, v[176:177] op_sel_hi:[1,0,1]
	v_pk_fma_f32 v[110:111], v[110:111], 0.5, v[174:175] op_sel_hi:[1,0,1]
	v_lshl_add_u64 v[120:121], v[118:119], 2, s[62:63]
	v_pk_fma_f32 v[108:109], v[108:109], 0.5, v[172:173] op_sel_hi:[1,0,1]
	v_pk_fma_f32 v[106:107], v[106:107], 0.5, v[170:171] op_sel_hi:[1,0,1]
	global_store_dwordx4 v[120:121], v[110:113], off nt
	global_store_dwordx4 v[120:121], v[106:109], off offset:16 nt
	v_cvt_pk_bf16_f32 v114, v110, v111
	v_cvt_pk_bf16_f32 v115, v112, v113
	v_cvt_pk_bf16_f32 v116, v106, v107
	v_pk_fma_f32 v[104:105], v[104:105], 0.5, v[168:169] op_sel_hi:[1,0,1]
	v_mul_f32_e32 v111, v111, v111
	v_fmac_f32_e32 v111, v110, v110
	v_mul_f32_e32 v110, v113, v113
	v_fmac_f32_e32 v110, v112, v112
	v_mul_f32_e32 v107, v107, v107
	v_add_f32_e32 v110, v111, v110
	v_fmac_f32_e32 v107, v106, v106
	v_add_f32_e32 v106, v110, v107
	v_mul_f32_e32 v107, v109, v109
	v_fmac_f32_e32 v107, v108, v108
	v_pk_fma_f32 v[102:103], v[102:103], 0.5, v[166:167] op_sel_hi:[1,0,1]
	v_cvt_pk_bf16_f32 v117, v108, v109
	v_add_f32_e32 v106, v107, v106
	v_mul_f32_e32 v107, v103, v103
	v_mul_f32_e32 v108, v105, v105
	v_pk_fma_f32 v[98:99], v[98:99], 0.5, v[162:163] op_sel_hi:[1,0,1]
	v_fmac_f32_e32 v107, v102, v102
	v_fmac_f32_e32 v108, v104, v104
	v_add_f32_e32 v107, v107, v108
	v_mul_f32_e32 v108, v99, v99
	v_pk_fma_f32 v[100:101], v[100:101], 0.5, v[164:165] op_sel_hi:[1,0,1]
	v_fmac_f32_e32 v108, v98, v98
	v_add_f32_e32 v107, v107, v108
	v_mul_f32_e32 v108, v101, v101
	v_fmac_f32_e32 v108, v100, v100
	v_add_f32_e32 v107, v108, v107
	v_add_f32_e32 v106, v106, v107
	ds_bpermute_b32 v107, v213, v106
	v_lshlrev_b64 v[118:119], 1, v[118:119]
	v_lshl_add_u64 v[124:125], s[2:3], 0, v[118:119]
	global_store_dwordx4 v[124:125], v[114:117], off nt
	global_store_dwordx4 v[120:121], v[102:105], off offset:512 nt
	global_store_dwordx4 v[120:121], v[98:101], off offset:528 nt
	v_or_b32_e32 v118, 0x100, v118
	v_cvt_pk_bf16_f32 v102, v102, v103
	v_cvt_pk_bf16_f32 v103, v104, v105
	v_cvt_pk_bf16_f32 v104, v98, v99
	v_cvt_pk_bf16_f32 v105, v100, v101
	s_waitcnt lgkmcnt(0)
	v_add_f32_e32 v98, v106, v107
	ds_bpermute_b32 v99, v122, v98
	v_lshl_add_u64 v[100:101], s[2:3], 0, v[118:119]
	global_store_dwordx4 v[100:101], v[102:105], off nt
	s_and_saveexec_b64 s[20:21], s[4:5]
	s_cbranch_execz .LBB0_299
	s_waitcnt lgkmcnt(0)
	v_add_f32_e32 v100, v98, v99
	v_lshlrev_b64 v[98:99], 6, v[204:205]
	v_lshl_add_u64 v[98:99], s[12:13], 0, v[98:99]
	v_lshl_add_u64 v[98:99], s[18:19], 2, v[98:99]
	s_lshl_b32 s16, s36, 2
	v_lshl_add_u64 v[98:99], v[98:99], 0, s[16:17]
	global_store_dword v[98:99], v100, off
.LBB0_299:
	s_or_b64 exec, exec, s[20:21]
	s_waitcnt lgkmcnt(0)
	v_lshlrev_b64 v[98:99], 10, v[202:203]
	v_lshl_add_u64 v[102:103], v[98:99], 0, v[194:195]
	v_pk_fma_f32 v[96:97], v[96:97], 0.5, v[160:161] op_sel_hi:[1,0,1]
	v_pk_fma_f32 v[94:95], v[94:95], 0.5, v[158:159] op_sel_hi:[1,0,1]
	v_lshl_add_u64 v[104:105], v[102:103], 2, s[62:63]
	v_pk_fma_f32 v[92:93], v[92:93], 0.5, v[156:157] op_sel_hi:[1,0,1]
	v_pk_fma_f32 v[90:91], v[90:91], 0.5, v[154:155] op_sel_hi:[1,0,1]
	global_store_dwordx4 v[104:105], v[94:97], off nt
	global_store_dwordx4 v[104:105], v[90:93], off offset:16 nt
	v_cvt_pk_bf16_f32 v98, v94, v95
	v_cvt_pk_bf16_f32 v99, v96, v97
	v_cvt_pk_bf16_f32 v100, v90, v91
	v_pk_fma_f32 v[88:89], v[88:89], 0.5, v[152:153] op_sel_hi:[1,0,1]
	v_mul_f32_e32 v95, v95, v95
	v_fmac_f32_e32 v95, v94, v94
	v_mul_f32_e32 v94, v97, v97
	v_fmac_f32_e32 v94, v96, v96
	v_mul_f32_e32 v91, v91, v91
	v_add_f32_e32 v94, v95, v94
	v_fmac_f32_e32 v91, v90, v90
	v_add_f32_e32 v90, v94, v91
	v_mul_f32_e32 v91, v93, v93
	v_fmac_f32_e32 v91, v92, v92
	v_pk_fma_f32 v[86:87], v[86:87], 0.5, v[150:151] op_sel_hi:[1,0,1]
	v_cvt_pk_bf16_f32 v101, v92, v93
	v_add_f32_e32 v90, v91, v90
	v_mul_f32_e32 v91, v87, v87
	v_mul_f32_e32 v92, v89, v89
	v_pk_fma_f32 v[82:83], v[82:83], 0.5, v[146:147] op_sel_hi:[1,0,1]
	v_fmac_f32_e32 v91, v86, v86
	v_fmac_f32_e32 v92, v88, v88
	v_add_f32_e32 v91, v91, v92
	v_mul_f32_e32 v92, v83, v83
	v_pk_fma_f32 v[84:85], v[84:85], 0.5, v[148:149] op_sel_hi:[1,0,1]
	v_fmac_f32_e32 v92, v82, v82
	v_add_f32_e32 v91, v91, v92
	v_mul_f32_e32 v92, v85, v85
	v_fmac_f32_e32 v92, v84, v84
	v_add_f32_e32 v91, v92, v91
	v_add_f32_e32 v90, v90, v91
	ds_bpermute_b32 v91, v213, v90
	v_lshlrev_b64 v[102:103], 1, v[102:103]
	v_lshl_add_u64 v[106:107], s[2:3], 0, v[102:103]
	global_store_dwordx4 v[106:107], v[98:101], off nt
	global_store_dwordx4 v[104:105], v[86:89], off offset:512 nt
	global_store_dwordx4 v[104:105], v[82:85], off offset:528 nt
	v_or_b32_e32 v102, 0x100, v102
	v_cvt_pk_bf16_f32 v86, v86, v87
	v_cvt_pk_bf16_f32 v87, v88, v89
	v_cvt_pk_bf16_f32 v88, v82, v83
	v_cvt_pk_bf16_f32 v89, v84, v85
	s_waitcnt lgkmcnt(0)
	v_add_f32_e32 v82, v90, v91
	ds_bpermute_b32 v83, v122, v82
	v_lshl_add_u64 v[84:85], s[2:3], 0, v[102:103]
	global_store_dwordx4 v[84:85], v[86:89], off nt
	s_and_saveexec_b64 s[20:21], s[4:5]
	s_cbranch_execz .LBB0_301
	s_waitcnt lgkmcnt(0)
	v_add_f32_e32 v84, v82, v83
	v_lshlrev_b64 v[82:83], 6, v[202:203]
	v_lshl_add_u64 v[82:83], s[12:13], 0, v[82:83]
	v_lshl_add_u64 v[82:83], s[18:19], 2, v[82:83]
	s_lshl_b32 s16, s36, 2
	v_lshl_add_u64 v[82:83], v[82:83], 0, s[16:17]
	global_store_dword v[82:83], v84, off
.LBB0_301:
	s_or_b64 exec, exec, s[20:21]
	s_waitcnt lgkmcnt(0)
	v_lshlrev_b64 v[82:83], 10, v[200:201]
	v_lshl_add_u64 v[86:87], v[82:83], 0, v[194:195]
	v_pk_fma_f32 v[80:81], v[80:81], 0.5, v[144:145] op_sel_hi:[1,0,1]
	v_pk_fma_f32 v[78:79], v[78:79], 0.5, v[142:143] op_sel_hi:[1,0,1]
	v_lshl_add_u64 v[88:89], v[86:87], 2, s[62:63]
	v_pk_fma_f32 v[76:77], v[76:77], 0.5, v[140:141] op_sel_hi:[1,0,1]
	v_pk_fma_f32 v[74:75], v[74:75], 0.5, v[138:139] op_sel_hi:[1,0,1]
	global_store_dwordx4 v[88:89], v[78:81], off nt
	global_store_dwordx4 v[88:89], v[74:77], off offset:16 nt
	v_cvt_pk_bf16_f32 v82, v78, v79
	v_cvt_pk_bf16_f32 v83, v80, v81
	v_cvt_pk_bf16_f32 v84, v74, v75
	v_pk_fma_f32 v[72:73], v[72:73], 0.5, v[136:137] op_sel_hi:[1,0,1]
	v_mul_f32_e32 v79, v79, v79
	v_fmac_f32_e32 v79, v78, v78
	v_mul_f32_e32 v78, v81, v81
	v_fmac_f32_e32 v78, v80, v80
	v_mul_f32_e32 v75, v75, v75
	v_add_f32_e32 v78, v79, v78
	v_fmac_f32_e32 v75, v74, v74
	v_add_f32_e32 v74, v78, v75
	v_mul_f32_e32 v75, v77, v77
	v_fmac_f32_e32 v75, v76, v76
	v_pk_fma_f32 v[70:71], v[70:71], 0.5, v[134:135] op_sel_hi:[1,0,1]
	v_cvt_pk_bf16_f32 v85, v76, v77
	v_add_f32_e32 v74, v75, v74
	v_mul_f32_e32 v75, v71, v71
	v_mul_f32_e32 v76, v73, v73
	v_pk_fma_f32 v[66:67], v[66:67], 0.5, v[130:131] op_sel_hi:[1,0,1]
	v_fmac_f32_e32 v75, v70, v70
	v_fmac_f32_e32 v76, v72, v72
	v_add_f32_e32 v75, v75, v76
	v_mul_f32_e32 v76, v67, v67
	v_pk_fma_f32 v[68:69], v[68:69], 0.5, v[132:133] op_sel_hi:[1,0,1]
	v_fmac_f32_e32 v76, v66, v66
	v_add_f32_e32 v75, v75, v76
	v_mul_f32_e32 v76, v69, v69
	v_fmac_f32_e32 v76, v68, v68
	v_add_f32_e32 v75, v76, v75
	v_add_f32_e32 v74, v74, v75
	ds_bpermute_b32 v75, v213, v74
	v_lshlrev_b64 v[86:87], 1, v[86:87]
	v_lshl_add_u64 v[90:91], s[2:3], 0, v[86:87]
	global_store_dwordx4 v[90:91], v[82:85], off nt
	global_store_dwordx4 v[88:89], v[70:73], off offset:512 nt
	global_store_dwordx4 v[88:89], v[66:69], off offset:528 nt
	v_or_b32_e32 v86, 0x100, v86
	v_cvt_pk_bf16_f32 v70, v70, v71
	v_cvt_pk_bf16_f32 v71, v72, v73
	v_cvt_pk_bf16_f32 v72, v66, v67
	v_cvt_pk_bf16_f32 v73, v68, v69
	s_waitcnt lgkmcnt(0)
	v_add_f32_e32 v66, v74, v75
	ds_bpermute_b32 v67, v122, v66
	v_lshl_add_u64 v[68:69], s[2:3], 0, v[86:87]
	global_store_dwordx4 v[68:69], v[70:73], off nt
	s_and_saveexec_b64 s[20:21], s[4:5]
	s_cbranch_execz .LBB0_303
	s_waitcnt lgkmcnt(0)
	v_add_f32_e32 v68, v66, v67
	v_lshlrev_b64 v[66:67], 6, v[200:201]
	v_lshl_add_u64 v[66:67], s[12:13], 0, v[66:67]
	v_lshl_add_u64 v[66:67], s[18:19], 2, v[66:67]
	s_lshl_b32 s16, s36, 2
	v_lshl_add_u64 v[66:67], v[66:67], 0, s[16:17]
	global_store_dword v[66:67], v68, off
.LBB0_303:
	s_or_b64 exec, exec, s[20:21]
	v_add_u32_e32 v120, 0x80, v198
	v_ashrrev_i32_e32 v121, 31, v120
	s_waitcnt lgkmcnt(0)
	v_lshlrev_b64 v[66:67], 12, v[120:121]
	v_lshl_add_u64 v[66:67], v[196:197], 0, v[66:67]
	global_load_dwordx4 v[124:127], v[66:67], off nt
	global_load_dwordx4 v[128:131], v[66:67], off offset:16 nt
	global_load_dwordx4 v[132:135], v[66:67], off offset:512 nt
	global_load_dwordx4 v[136:139], v[66:67], off offset:528 nt
	v_add_u32_e32 v118, 0x90, v198
	v_add_u32_e32 v116, 0xa0, v198
	v_add_u32_e32 v114, 0xb0, v198
	v_ashrrev_i32_e32 v119, 31, v118
	v_ashrrev_i32_e32 v117, 31, v116
	v_ashrrev_i32_e32 v115, 31, v114
	v_lshlrev_b64 v[66:67], 12, v[118:119]
	v_lshlrev_b64 v[68:69], 12, v[116:117]
	v_lshlrev_b64 v[70:71], 12, v[114:115]
	v_lshl_add_u64 v[66:67], v[196:197], 0, v[66:67]
	v_lshl_add_u64 v[68:69], v[196:197], 0, v[68:69]
	v_lshl_add_u64 v[70:71], v[196:197], 0, v[70:71]
	global_load_dwordx4 v[106:109], v[66:67], off offset:16 nt
	global_load_dwordx4 v[110:113], v[66:67], off nt
	global_load_dwordx4 v[98:101], v[66:67], off offset:528 nt
	global_load_dwordx4 v[102:105], v[66:67], off offset:512 nt
	global_load_dwordx4 v[90:93], v[68:69], off offset:16 nt
	global_load_dwordx4 v[94:97], v[68:69], off nt
	global_load_dwordx4 v[82:85], v[68:69], off offset:528 nt
	global_load_dwordx4 v[86:89], v[68:69], off offset:512 nt
	global_load_dwordx4 v[74:77], v[70:71], off offset:16 nt
	global_load_dwordx4 v[78:81], v[70:71], off nt
	s_nop 0
	global_load_dwordx4 v[66:69], v[70:71], off offset:528 nt
	s_nop 0
	global_load_dwordx4 v[70:73], v[70:71], off offset:512 nt
	v_lshlrev_b64 v[140:141], 10, v[120:121]
	v_lshl_add_u64 v[140:141], v[140:141], 0, v[194:195]
	v_lshl_add_u64 v[142:143], v[140:141], 2, s[62:63]
	v_lshlrev_b64 v[140:141], 1, v[140:141]
	v_lshl_add_u64 v[144:145], s[2:3], 0, v[140:141]
	v_or_b32_e32 v140, 0x100, v140
	s_waitcnt vmcnt(15)
	v_pk_fma_f32 v[64:65], v[64:65], 0.5, v[126:127] op_sel_hi:[1,0,1]
	v_pk_fma_f32 v[62:63], v[62:63], 0.5, v[124:125] op_sel_hi:[1,0,1]
	s_waitcnt vmcnt(13)
	v_pk_fma_f32 v[56:57], v[56:57], 0.5, v[134:135] op_sel_hi:[1,0,1]
	v_pk_fma_f32 v[54:55], v[54:55], 0.5, v[132:133] op_sel_hi:[1,0,1]
	v_pk_fma_f32 v[60:61], v[60:61], 0.5, v[130:131] op_sel_hi:[1,0,1]
	v_pk_fma_f32 v[58:59], v[58:59], 0.5, v[128:129] op_sel_hi:[1,0,1]
	s_waitcnt vmcnt(12)
	v_pk_fma_f32 v[50:51], v[50:51], 0.5, v[136:137] op_sel_hi:[1,0,1]
	global_store_dwordx4 v[142:143], v[62:65], off nt
	global_store_dwordx4 v[142:143], v[58:61], off offset:16 nt
	v_cvt_pk_bf16_f32 v124, v62, v63
	v_cvt_pk_bf16_f32 v125, v64, v65
	v_mul_f32_e32 v123, v55, v55
	v_mul_f32_e32 v63, v63, v63
	v_mul_f32_e32 v65, v65, v65
	v_mul_f32_e32 v128, v57, v57
	v_pk_fma_f32 v[52:53], v[52:53], 0.5, v[138:139] op_sel_hi:[1,0,1]
	v_cvt_pk_bf16_f32 v126, v58, v59
	v_cvt_pk_bf16_f32 v127, v60, v61
	v_mul_f32_e32 v59, v59, v59
	v_mul_f32_e32 v61, v61, v61
	v_mul_f32_e32 v129, v51, v51
	v_fmac_f32_e32 v63, v62, v62
	v_fmac_f32_e32 v65, v64, v64
	v_fmac_f32_e32 v123, v54, v54
	v_fmac_f32_e32 v128, v56, v56
	v_mul_f32_e32 v130, v53, v53
	v_fmac_f32_e32 v59, v58, v58
	v_fmac_f32_e32 v61, v60, v60
	v_fmac_f32_e32 v129, v50, v50
	v_add_f32_e32 v58, v63, v65
	v_add_f32_e32 v60, v123, v128
	v_fmac_f32_e32 v130, v52, v52
	v_add_f32_e32 v58, v58, v59
	v_add_f32_e32 v59, v60, v129
	v_add_f32_e32 v58, v61, v58
	v_add_f32_e32 v59, v130, v59
	v_add_f32_e32 v58, v58, v59
	ds_bpermute_b32 v59, v213, v58
	global_store_dwordx4 v[144:145], v[124:127], off nt
	global_store_dwordx4 v[142:143], v[54:57], off offset:512 nt
	global_store_dwordx4 v[142:143], v[50:53], off offset:528 nt
	s_nop 0
	v_cvt_pk_bf16_f32 v54, v54, v55
	v_cvt_pk_bf16_f32 v55, v56, v57
	v_cvt_pk_bf16_f32 v56, v50, v51
	v_cvt_pk_bf16_f32 v57, v52, v53
	s_waitcnt lgkmcnt(0)
	v_add_f32_e32 v50, v58, v59
	ds_bpermute_b32 v51, v122, v50
	v_lshl_add_u64 v[52:53], s[2:3], 0, v[140:141]
	global_store_dwordx4 v[52:53], v[54:57], off nt
	s_and_saveexec_b64 s[20:21], s[4:5]
	s_cbranch_execz .LBB0_305
	s_waitcnt lgkmcnt(0)
	v_add_f32_e32 v52, v50, v51
	v_lshlrev_b64 v[50:51], 6, v[120:121]
	v_lshl_add_u64 v[50:51], s[12:13], 0, v[50:51]
	v_lshl_add_u64 v[50:51], s[18:19], 2, v[50:51]
	s_lshl_b32 s16, s36, 2
	v_lshl_add_u64 v[50:51], v[50:51], 0, s[16:17]
	global_store_dword v[50:51], v52, off
.LBB0_305:
	s_or_b64 exec, exec, s[20:21]
	s_waitcnt lgkmcnt(0)
	v_lshlrev_b64 v[50:51], 10, v[118:119]
	v_lshl_add_u64 v[54:55], v[50:51], 0, v[194:195]
	s_waitcnt vmcnt(16)
	v_pk_fma_f32 v[48:49], v[48:49], 0.5, v[112:113] op_sel_hi:[1,0,1]
	v_pk_fma_f32 v[46:47], v[46:47], 0.5, v[110:111] op_sel_hi:[1,0,1]
	v_lshl_add_u64 v[56:57], v[54:55], 2, s[62:63]
	v_pk_fma_f32 v[44:45], v[44:45], 0.5, v[108:109] op_sel_hi:[1,0,1]
	v_pk_fma_f32 v[42:43], v[42:43], 0.5, v[106:107] op_sel_hi:[1,0,1]
	global_store_dwordx4 v[56:57], v[46:49], off nt
	global_store_dwordx4 v[56:57], v[42:45], off offset:16 nt
	v_cvt_pk_bf16_f32 v50, v46, v47
	v_cvt_pk_bf16_f32 v51, v48, v49
	v_cvt_pk_bf16_f32 v52, v42, v43
	s_waitcnt vmcnt(16)
	v_pk_fma_f32 v[40:41], v[40:41], 0.5, v[104:105] op_sel_hi:[1,0,1]
	v_mul_f32_e32 v47, v47, v47
	v_fmac_f32_e32 v47, v46, v46
	v_mul_f32_e32 v46, v49, v49
	v_fmac_f32_e32 v46, v48, v48
	v_mul_f32_e32 v43, v43, v43
	v_add_f32_e32 v46, v47, v46
	v_fmac_f32_e32 v43, v42, v42
	v_add_f32_e32 v42, v46, v43
	v_mul_f32_e32 v43, v45, v45
	v_fmac_f32_e32 v43, v44, v44
	v_pk_fma_f32 v[38:39], v[38:39], 0.5, v[102:103] op_sel_hi:[1,0,1]
	v_cvt_pk_bf16_f32 v53, v44, v45
	v_add_f32_e32 v42, v43, v42
	v_mul_f32_e32 v43, v39, v39
	v_mul_f32_e32 v44, v41, v41
	v_pk_fma_f32 v[34:35], v[34:35], 0.5, v[98:99] op_sel_hi:[1,0,1]
	v_fmac_f32_e32 v43, v38, v38
	v_fmac_f32_e32 v44, v40, v40
	v_add_f32_e32 v43, v43, v44
	v_mul_f32_e32 v44, v35, v35
	v_pk_fma_f32 v[36:37], v[36:37], 0.5, v[100:101] op_sel_hi:[1,0,1]
	v_fmac_f32_e32 v44, v34, v34
	v_add_f32_e32 v43, v43, v44
	v_mul_f32_e32 v44, v37, v37
	v_fmac_f32_e32 v44, v36, v36
	v_add_f32_e32 v43, v44, v43
	v_add_f32_e32 v42, v42, v43
	ds_bpermute_b32 v43, v213, v42
	v_lshlrev_b64 v[54:55], 1, v[54:55]
	v_lshl_add_u64 v[58:59], s[2:3], 0, v[54:55]
	global_store_dwordx4 v[58:59], v[50:53], off nt
	global_store_dwordx4 v[56:57], v[38:41], off offset:512 nt
	global_store_dwordx4 v[56:57], v[34:37], off offset:528 nt
	v_or_b32_e32 v54, 0x100, v54
	v_cvt_pk_bf16_f32 v38, v38, v39
	v_cvt_pk_bf16_f32 v39, v40, v41
	v_cvt_pk_bf16_f32 v40, v34, v35
	v_cvt_pk_bf16_f32 v41, v36, v37
	s_waitcnt lgkmcnt(0)
	v_add_f32_e32 v34, v42, v43
	ds_bpermute_b32 v35, v122, v34
	v_lshl_add_u64 v[36:37], s[2:3], 0, v[54:55]
	global_store_dwordx4 v[36:37], v[38:41], off nt
	s_and_saveexec_b64 s[20:21], s[4:5]
	s_cbranch_execz .LBB0_307
	s_waitcnt lgkmcnt(0)
	v_add_f32_e32 v36, v34, v35
	v_lshlrev_b64 v[34:35], 6, v[118:119]
	v_lshl_add_u64 v[34:35], s[12:13], 0, v[34:35]
	v_lshl_add_u64 v[34:35], s[18:19], 2, v[34:35]
	s_lshl_b32 s16, s36, 2
	v_lshl_add_u64 v[34:35], v[34:35], 0, s[16:17]
	global_store_dword v[34:35], v36, off
.LBB0_307:
	s_or_b64 exec, exec, s[20:21]
	s_waitcnt lgkmcnt(0)
	v_lshlrev_b64 v[34:35], 10, v[116:117]
	v_lshl_add_u64 v[38:39], v[34:35], 0, v[194:195]
	s_waitcnt vmcnt(18)
	v_pk_fma_f32 v[32:33], v[32:33], 0.5, v[96:97] op_sel_hi:[1,0,1]
	v_pk_fma_f32 v[30:31], v[30:31], 0.5, v[94:95] op_sel_hi:[1,0,1]
	v_lshl_add_u64 v[40:41], v[38:39], 2, s[62:63]
	v_pk_fma_f32 v[28:29], v[28:29], 0.5, v[92:93] op_sel_hi:[1,0,1]
	v_pk_fma_f32 v[26:27], v[26:27], 0.5, v[90:91] op_sel_hi:[1,0,1]
	global_store_dwordx4 v[40:41], v[30:33], off nt
	global_store_dwordx4 v[40:41], v[26:29], off offset:16 nt
	v_cvt_pk_bf16_f32 v34, v30, v31
	v_cvt_pk_bf16_f32 v35, v32, v33
	v_cvt_pk_bf16_f32 v36, v26, v27
	s_waitcnt vmcnt(18)
	v_pk_fma_f32 v[24:25], v[24:25], 0.5, v[88:89] op_sel_hi:[1,0,1]
	v_mul_f32_e32 v31, v31, v31
	v_fmac_f32_e32 v31, v30, v30
	v_mul_f32_e32 v30, v33, v33
	v_fmac_f32_e32 v30, v32, v32
	v_mul_f32_e32 v27, v27, v27
	v_add_f32_e32 v30, v31, v30
	v_fmac_f32_e32 v27, v26, v26
	v_add_f32_e32 v26, v30, v27
	v_mul_f32_e32 v27, v29, v29
	v_fmac_f32_e32 v27, v28, v28
	v_pk_fma_f32 v[22:23], v[22:23], 0.5, v[86:87] op_sel_hi:[1,0,1]
	v_cvt_pk_bf16_f32 v37, v28, v29
	v_add_f32_e32 v26, v27, v26
	v_mul_f32_e32 v27, v23, v23
	v_mul_f32_e32 v28, v25, v25
	v_pk_fma_f32 v[18:19], v[18:19], 0.5, v[82:83] op_sel_hi:[1,0,1]
	v_fmac_f32_e32 v27, v22, v22
	v_fmac_f32_e32 v28, v24, v24
	v_add_f32_e32 v27, v27, v28
	v_mul_f32_e32 v28, v19, v19
	v_pk_fma_f32 v[20:21], v[20:21], 0.5, v[84:85] op_sel_hi:[1,0,1]
	v_fmac_f32_e32 v28, v18, v18
	v_add_f32_e32 v27, v27, v28
	v_mul_f32_e32 v28, v21, v21
	v_fmac_f32_e32 v28, v20, v20
	v_add_f32_e32 v27, v28, v27
	v_add_f32_e32 v26, v26, v27
	ds_bpermute_b32 v27, v213, v26
	v_lshlrev_b64 v[38:39], 1, v[38:39]
	v_lshl_add_u64 v[42:43], s[2:3], 0, v[38:39]
	global_store_dwordx4 v[42:43], v[34:37], off nt
	global_store_dwordx4 v[40:41], v[22:25], off offset:512 nt
	global_store_dwordx4 v[40:41], v[18:21], off offset:528 nt
	v_or_b32_e32 v38, 0x100, v38
	v_cvt_pk_bf16_f32 v22, v22, v23
	v_cvt_pk_bf16_f32 v23, v24, v25
	v_cvt_pk_bf16_f32 v24, v18, v19
	v_cvt_pk_bf16_f32 v25, v20, v21
	s_waitcnt lgkmcnt(0)
	v_add_f32_e32 v18, v26, v27
	ds_bpermute_b32 v19, v122, v18
	v_lshl_add_u64 v[20:21], s[2:3], 0, v[38:39]
	global_store_dwordx4 v[20:21], v[22:25], off nt
	s_and_saveexec_b64 s[20:21], s[4:5]
	s_cbranch_execz .LBB0_309
	s_waitcnt lgkmcnt(0)
	v_add_f32_e32 v20, v18, v19
	v_lshlrev_b64 v[18:19], 6, v[116:117]
	v_lshl_add_u64 v[18:19], s[12:13], 0, v[18:19]
	v_lshl_add_u64 v[18:19], s[18:19], 2, v[18:19]
	s_lshl_b32 s16, s36, 2
	v_lshl_add_u64 v[18:19], v[18:19], 0, s[16:17]
	global_store_dword v[18:19], v20, off
.LBB0_309:
	s_or_b64 exec, exec, s[20:21]
	s_waitcnt lgkmcnt(0)
	v_lshlrev_b64 v[18:19], 10, v[114:115]
	v_lshl_add_u64 v[22:23], v[18:19], 0, v[194:195]
	s_waitcnt vmcnt(20)
	v_pk_fma_f32 v[16:17], v[16:17], 0.5, v[80:81] op_sel_hi:[1,0,1]
	v_pk_fma_f32 v[14:15], v[14:15], 0.5, v[78:79] op_sel_hi:[1,0,1]
	v_lshl_add_u64 v[24:25], v[22:23], 2, s[62:63]
	v_pk_fma_f32 v[12:13], v[12:13], 0.5, v[76:77] op_sel_hi:[1,0,1]
	v_pk_fma_f32 v[10:11], v[10:11], 0.5, v[74:75] op_sel_hi:[1,0,1]
	global_store_dwordx4 v[24:25], v[14:17], off nt
	global_store_dwordx4 v[24:25], v[10:13], off offset:16 nt
	v_cvt_pk_bf16_f32 v18, v14, v15
	v_cvt_pk_bf16_f32 v19, v16, v17
	v_cvt_pk_bf16_f32 v20, v10, v11
	s_waitcnt vmcnt(20)
	v_pk_fma_f32 v[8:9], v[8:9], 0.5, v[72:73] op_sel_hi:[1,0,1]
	v_mul_f32_e32 v15, v15, v15
	v_fmac_f32_e32 v15, v14, v14
	v_mul_f32_e32 v14, v17, v17
	v_fmac_f32_e32 v14, v16, v16
	v_mul_f32_e32 v11, v11, v11
	v_add_f32_e32 v14, v15, v14
	v_fmac_f32_e32 v11, v10, v10
	v_add_f32_e32 v10, v14, v11
	v_mul_f32_e32 v11, v13, v13
	v_fmac_f32_e32 v11, v12, v12
	v_pk_fma_f32 v[6:7], v[6:7], 0.5, v[70:71] op_sel_hi:[1,0,1]
	v_cvt_pk_bf16_f32 v21, v12, v13
	v_add_f32_e32 v10, v11, v10
	v_mul_f32_e32 v11, v7, v7
	v_mul_f32_e32 v12, v9, v9
	v_pk_fma_f32 v[2:3], v[2:3], 0.5, v[66:67] op_sel_hi:[1,0,1]
	v_fmac_f32_e32 v11, v6, v6
	v_fmac_f32_e32 v12, v8, v8
	v_add_f32_e32 v11, v11, v12
	v_mul_f32_e32 v12, v3, v3
	v_pk_fma_f32 v[4:5], v[4:5], 0.5, v[68:69] op_sel_hi:[1,0,1]
	v_fmac_f32_e32 v12, v2, v2
	v_add_f32_e32 v11, v11, v12
	v_mul_f32_e32 v12, v5, v5
	v_fmac_f32_e32 v12, v4, v4
	v_add_f32_e32 v11, v12, v11
	v_add_f32_e32 v10, v10, v11
	ds_bpermute_b32 v11, v213, v10
	v_lshlrev_b64 v[22:23], 1, v[22:23]
	v_lshl_add_u64 v[26:27], s[2:3], 0, v[22:23]
	global_store_dwordx4 v[26:27], v[18:21], off nt
	global_store_dwordx4 v[24:25], v[6:9], off offset:512 nt
	global_store_dwordx4 v[24:25], v[2:5], off offset:528 nt
	v_or_b32_e32 v22, 0x100, v22
	v_cvt_pk_bf16_f32 v6, v6, v7
	v_cvt_pk_bf16_f32 v7, v8, v9
	v_cvt_pk_bf16_f32 v8, v2, v3
	v_cvt_pk_bf16_f32 v9, v4, v5
	s_waitcnt lgkmcnt(0)
	v_add_f32_e32 v2, v10, v11
	ds_bpermute_b32 v3, v122, v2
	v_lshl_add_u64 v[4:5], s[2:3], 0, v[22:23]
	global_store_dwordx4 v[4:5], v[6:9], off nt
	s_and_saveexec_b64 s[20:21], s[4:5]
	s_cbranch_execz .LBB0_282
	s_waitcnt lgkmcnt(0)
	v_add_f32_e32 v4, v2, v3
	v_lshlrev_b64 v[2:3], 6, v[114:115]
	v_lshl_add_u64 v[2:3], s[12:13], 0, v[2:3]
	v_lshl_add_u64 v[2:3], s[18:19], 2, v[2:3]
	s_lshl_b32 s16, s36, 2
	v_lshl_add_u64 v[2:3], v[2:3], 0, s[16:17]
	global_store_dword v[2:3], v4, off
	s_branch .LBB0_282

.LBB0_2387:
	ds_read_b128 v[130:133], v213
	ds_read_b128 v[134:137], v213 offset:1024
	ds_read_b128 v[138:141], v213 offset:2048
	ds_read_b128 v[142:145], v213 offset:3072
	ds_read_b128 v[146:149], v214
	ds_read_b128 v[150:153], v214 offset:1024
	ds_read_b128 v[154:157], v214 offset:2048
	ds_read_b128 v[158:161], v214 offset:3072
	s_add_u32 s26, s24, 0xfffc0080
	s_addc_u32 s27, s25, -1
	s_cmp_eq_u32 s55, 12
	s_cselect_b32 s29, s17, s27
	s_cselect_b32 s28, s23, s26
	s_cselect_b32 s27, s15, s54
	s_cselect_b32 s26, s52, s53
	v_lshl_add_u64 v[210:211], s[24:25], 0, v[186:187]
	s_add_i32 m0, s38, 0xc000
	ds_read_b128 v[162:165], v215
	ds_read_b128 v[166:169], v215 offset:1024
	ds_read_b128 v[170:173], v215 offset:2048
	ds_read_b128 v[174:177], v215 offset:3072
	ds_read_b128 v[194:197], v215 offset:4096
	ds_read_b128 v[198:201], v215 offset:5120
	ds_read_b128 v[202:205], v215 offset:6144
	ds_read_b128 v[206:209], v215 offset:7168
	global_load_lds_dwordx4 v[210:211], off
	v_lshl_add_u64 v[210:211], s[24:25], 0, v[188:189]
	s_add_i32 m0, s38, 0xe000
	s_nop 0
	global_load_lds_dwordx4 v[210:211], off
	s_waitcnt vmcnt(8)
	s_waitcnt lgkmcnt(0)
	s_barrier
	s_setprio 1
	s_waitcnt lgkmcnt(0)
	v_mfma_f32_16x16x32_bf16 v[126:129], v[130:133], v[162:165], v[126:129]
	v_mfma_f32_16x16x32_bf16 v[122:125], v[138:141], v[162:165], v[122:125]
	v_mfma_f32_16x16x32_bf16 v[110:113], v[130:133], v[170:173], v[110:113]
	v_mfma_f32_16x16x32_bf16 v[106:109], v[138:141], v[170:173], v[106:109]
	v_mfma_f32_16x16x32_bf16 v[94:97], v[130:133], v[194:197], v[94:97]
	v_mfma_f32_16x16x32_bf16 v[90:93], v[138:141], v[194:197], v[90:93]
	v_mfma_f32_16x16x32_bf16 v[78:81], v[130:133], v[202:205], v[78:81]
	v_mfma_f32_16x16x32_bf16 v[74:77], v[138:141], v[202:205], v[74:77]
	v_mfma_f32_16x16x32_bf16 v[126:129], v[134:137], v[166:169], v[126:129]
	v_mfma_f32_16x16x32_bf16 v[122:125], v[142:145], v[166:169], v[122:125]
	v_mfma_f32_16x16x32_bf16 v[110:113], v[134:137], v[174:177], v[110:113]
	v_mfma_f32_16x16x32_bf16 v[106:109], v[142:145], v[174:177], v[106:109]
	v_mfma_f32_16x16x32_bf16 v[94:97], v[134:137], v[198:201], v[94:97]
	v_mfma_f32_16x16x32_bf16 v[90:93], v[142:145], v[198:201], v[90:93]
	v_mfma_f32_16x16x32_bf16 v[78:81], v[134:137], v[206:209], v[78:81]
	v_mfma_f32_16x16x32_bf16 v[74:77], v[142:145], v[206:209], v[74:77]
	s_setprio 0
	s_setprio 1
	v_mfma_f32_16x16x32_bf16 v[118:121], v[146:149], v[162:165], v[118:121]
	v_mfma_f32_16x16x32_bf16 v[114:117], v[154:157], v[162:165], v[114:117]
	v_mfma_f32_16x16x32_bf16 v[102:105], v[146:149], v[170:173], v[102:105]
	v_mfma_f32_16x16x32_bf16 v[98:101], v[154:157], v[170:173], v[98:101]
	v_mfma_f32_16x16x32_bf16 v[86:89], v[146:149], v[194:197], v[86:89]
	v_mfma_f32_16x16x32_bf16 v[82:85], v[154:157], v[194:197], v[82:85]
	v_mfma_f32_16x16x32_bf16 v[70:73], v[146:149], v[202:205], v[70:73]
	v_mfma_f32_16x16x32_bf16 v[66:69], v[154:157], v[202:205], v[66:69]
	v_mfma_f32_16x16x32_bf16 v[118:121], v[150:153], v[166:169], v[118:121]
	v_mfma_f32_16x16x32_bf16 v[114:117], v[158:161], v[166:169], v[114:117]
	v_mfma_f32_16x16x32_bf16 v[102:105], v[150:153], v[174:177], v[102:105]
	v_mfma_f32_16x16x32_bf16 v[98:101], v[158:161], v[174:177], v[98:101]
	v_mfma_f32_16x16x32_bf16 v[86:89], v[150:153], v[198:201], v[86:89]
	v_mfma_f32_16x16x32_bf16 v[82:85], v[158:161], v[198:201], v[82:85]
	v_mfma_f32_16x16x32_bf16 v[70:73], v[150:153], v[206:209], v[70:73]
	v_mfma_f32_16x16x32_bf16 v[66:69], v[158:161], v[206:209], v[66:69]
	s_setprio 0
	s_barrier
	s_add_i32 s56, s47, s37
	v_lshl_add_u64 v[210:211], s[26:27], 0, v[180:181]
	s_mov_b32 m0, s56
	ds_read_b128 v[162:165], v215 offset:16384
	ds_read_b128 v[166:169], v215 offset:17408
	ds_read_b128 v[170:173], v215 offset:18432
	ds_read_b128 v[174:177], v215 offset:19456
	ds_read_b128 v[194:197], v215 offset:20480
	ds_read_b128 v[198:201], v215 offset:21504
	ds_read_b128 v[202:205], v215 offset:22528
	ds_read_b128 v[206:209], v215 offset:23552
	global_load_lds_dwordx4 v[210:211], off
	s_add_i32 m0, s56, 0x2000
	s_add_u32 s56, s26, 0x40000
	v_lshl_add_u64 v[220:221], s[26:27], 0, v[184:185]
	s_addc_u32 s57, s27, 0
	s_add_i32 s58, s48, s37
	global_load_lds_dwordx4 v[220:221], off
	v_lshl_add_u64 v[222:223], s[56:57], 0, v[180:181]
	s_mov_b32 m0, s58
	v_lshl_add_u64 v[224:225], s[28:29], 0, v[182:183]
	global_load_lds_dwordx4 v[222:223], off
	v_lshl_add_u64 v[222:223], s[56:57], 0, v[184:185]
	s_add_i32 m0, s58, 0x2000
	s_nop 0
	global_load_lds_dwordx4 v[222:223], off
	v_lshl_add_u64 v[222:223], s[28:29], 0, v[178:179]
	s_mov_b32 m0, s38
	s_nop 0
	global_load_lds_dwordx4 v[222:223], off
	s_mov_b32 m0, s39
	s_nop 0
	global_load_lds_dwordx4 v[224:225], off
	s_waitcnt vmcnt(8)
	s_waitcnt lgkmcnt(0)
	s_barrier
	s_setprio 1
	s_waitcnt lgkmcnt(0)
	v_mfma_f32_16x16x32_bf16 v[62:65], v[130:133], v[162:165], v[62:65]
	v_mfma_f32_16x16x32_bf16 v[58:61], v[138:141], v[162:165], v[58:61]
	v_mfma_f32_16x16x32_bf16 v[46:49], v[130:133], v[170:173], v[46:49]
	v_mfma_f32_16x16x32_bf16 v[42:45], v[138:141], v[170:173], v[42:45]
	v_mfma_f32_16x16x32_bf16 v[30:33], v[130:133], v[194:197], v[30:33]
	v_mfma_f32_16x16x32_bf16 v[26:29], v[138:141], v[194:197], v[26:29]
	v_mfma_f32_16x16x32_bf16 v[14:17], v[130:133], v[202:205], v[14:17]
	v_mfma_f32_16x16x32_bf16 v[10:13], v[138:141], v[202:205], v[10:13]
	v_mfma_f32_16x16x32_bf16 v[62:65], v[134:137], v[166:169], v[62:65]
	v_mfma_f32_16x16x32_bf16 v[58:61], v[142:145], v[166:169], v[58:61]
	v_mfma_f32_16x16x32_bf16 v[46:49], v[134:137], v[174:177], v[46:49]
	v_mfma_f32_16x16x32_bf16 v[42:45], v[142:145], v[174:177], v[42:45]
	v_mfma_f32_16x16x32_bf16 v[30:33], v[134:137], v[198:201], v[30:33]
	v_mfma_f32_16x16x32_bf16 v[26:29], v[142:145], v[198:201], v[26:29]
	v_mfma_f32_16x16x32_bf16 v[14:17], v[134:137], v[206:209], v[14:17]
	v_mfma_f32_16x16x32_bf16 v[10:13], v[142:145], v[206:209], v[10:13]
	s_setprio 0
	s_setprio 1
	v_mfma_f32_16x16x32_bf16 v[54:57], v[146:149], v[162:165], v[54:57]
	v_mfma_f32_16x16x32_bf16 v[50:53], v[154:157], v[162:165], v[50:53]
	v_mfma_f32_16x16x32_bf16 v[38:41], v[146:149], v[170:173], v[38:41]
	v_mfma_f32_16x16x32_bf16 v[34:37], v[154:157], v[170:173], v[34:37]
	v_mfma_f32_16x16x32_bf16 v[22:25], v[146:149], v[194:197], v[22:25]
	v_mfma_f32_16x16x32_bf16 v[18:21], v[154:157], v[194:197], v[18:21]
	v_mfma_f32_16x16x32_bf16 v[6:9], v[146:149], v[202:205], v[6:9]
	v_mfma_f32_16x16x32_bf16 v[2:5], v[154:157], v[202:205], v[2:5]
	v_mfma_f32_16x16x32_bf16 v[54:57], v[150:153], v[166:169], v[54:57]
	v_mfma_f32_16x16x32_bf16 v[50:53], v[158:161], v[166:169], v[50:53]
	v_mfma_f32_16x16x32_bf16 v[38:41], v[150:153], v[174:177], v[38:41]
	v_mfma_f32_16x16x32_bf16 v[34:37], v[158:161], v[174:177], v[34:37]
	v_mfma_f32_16x16x32_bf16 v[22:25], v[150:153], v[198:201], v[22:25]
	v_mfma_f32_16x16x32_bf16 v[18:21], v[158:161], v[198:201], v[18:21]
	v_mfma_f32_16x16x32_bf16 v[6:9], v[150:153], v[206:209], v[6:9]
	v_mfma_f32_16x16x32_bf16 v[2:5], v[158:161], v[206:209], v[2:5]
	s_setprio 0
	s_barrier
	ds_read_b128 v[130:133], v217
	ds_read_b128 v[134:137], v217 offset:1024
	ds_read_b128 v[138:141], v217 offset:2048
	ds_read_b128 v[142:145], v217 offset:3072
	ds_read_b128 v[146:149], v218
	ds_read_b128 v[150:153], v218 offset:1024
	ds_read_b128 v[154:157], v218 offset:2048
	ds_read_b128 v[158:161], v218 offset:3072
	s_add_u32 s28, s28, 0x40000
	s_addc_u32 s29, s29, 0
	s_mov_b32 m0, s40
	v_lshl_add_u64 v[226:227], s[28:29], 0, v[178:179]
	ds_read_b128 v[162:165], v215 offset:32768
	ds_read_b128 v[166:169], v215 offset:33792
	ds_read_b128 v[170:173], v215 offset:34816
	ds_read_b128 v[174:177], v215 offset:35840
	ds_read_b128 v[194:197], v215 offset:36864
	ds_read_b128 v[198:201], v215 offset:37888
	ds_read_b128 v[202:205], v215 offset:38912
	ds_read_b128 v[206:209], v215 offset:39936
	global_load_lds_dwordx4 v[226:227], off
	v_lshl_add_u64 v[226:227], s[28:29], 0, v[182:183]
	s_mov_b32 m0, s41
	s_nop 0
	global_load_lds_dwordx4 v[226:227], off
	s_waitcnt vmcnt(8)
	s_waitcnt lgkmcnt(0)
	s_barrier
	s_setprio 1
	s_waitcnt lgkmcnt(0)
	v_mfma_f32_16x16x32_bf16 v[126:129], v[130:133], v[162:165], v[126:129]
	v_mfma_f32_16x16x32_bf16 v[122:125], v[138:141], v[162:165], v[122:125]
	v_mfma_f32_16x16x32_bf16 v[110:113], v[130:133], v[170:173], v[110:113]
	v_mfma_f32_16x16x32_bf16 v[106:109], v[138:141], v[170:173], v[106:109]
	v_mfma_f32_16x16x32_bf16 v[94:97], v[130:133], v[194:197], v[94:97]
	v_mfma_f32_16x16x32_bf16 v[90:93], v[138:141], v[194:197], v[90:93]
	v_mfma_f32_16x16x32_bf16 v[78:81], v[130:133], v[202:205], v[78:81]
	v_mfma_f32_16x16x32_bf16 v[74:77], v[138:141], v[202:205], v[74:77]
	v_mfma_f32_16x16x32_bf16 v[126:129], v[134:137], v[166:169], v[126:129]
	v_mfma_f32_16x16x32_bf16 v[122:125], v[142:145], v[166:169], v[122:125]
	v_mfma_f32_16x16x32_bf16 v[110:113], v[134:137], v[174:177], v[110:113]
	v_mfma_f32_16x16x32_bf16 v[106:109], v[142:145], v[174:177], v[106:109]
	v_mfma_f32_16x16x32_bf16 v[94:97], v[134:137], v[198:201], v[94:97]
	v_mfma_f32_16x16x32_bf16 v[90:93], v[142:145], v[198:201], v[90:93]
	v_mfma_f32_16x16x32_bf16 v[78:81], v[134:137], v[206:209], v[78:81]
	v_mfma_f32_16x16x32_bf16 v[74:77], v[142:145], v[206:209], v[74:77]
	s_setprio 0
	s_setprio 1
	v_mfma_f32_16x16x32_bf16 v[118:121], v[146:149], v[162:165], v[118:121]
	v_mfma_f32_16x16x32_bf16 v[114:117], v[154:157], v[162:165], v[114:117]
	v_mfma_f32_16x16x32_bf16 v[102:105], v[146:149], v[170:173], v[102:105]
	v_mfma_f32_16x16x32_bf16 v[98:101], v[154:157], v[170:173], v[98:101]
	v_mfma_f32_16x16x32_bf16 v[86:89], v[146:149], v[194:197], v[86:89]
	v_mfma_f32_16x16x32_bf16 v[82:85], v[154:157], v[194:197], v[82:85]
	v_mfma_f32_16x16x32_bf16 v[70:73], v[146:149], v[202:205], v[70:73]
	v_mfma_f32_16x16x32_bf16 v[66:69], v[154:157], v[202:205], v[66:69]
	v_mfma_f32_16x16x32_bf16 v[118:121], v[150:153], v[166:169], v[118:121]
	v_mfma_f32_16x16x32_bf16 v[114:117], v[158:161], v[166:169], v[114:117]
	v_mfma_f32_16x16x32_bf16 v[102:105], v[150:153], v[174:177], v[102:105]
	v_mfma_f32_16x16x32_bf16 v[98:101], v[158:161], v[174:177], v[98:101]
	v_mfma_f32_16x16x32_bf16 v[86:89], v[150:153], v[198:201], v[86:89]
	v_mfma_f32_16x16x32_bf16 v[82:85], v[158:161], v[198:201], v[82:85]
	v_mfma_f32_16x16x32_bf16 v[70:73], v[150:153], v[206:209], v[70:73]
	v_mfma_f32_16x16x32_bf16 v[66:69], v[158:161], v[206:209], v[66:69]
	s_setprio 0
	s_barrier
	s_add_i32 s28, s49, s37
	v_lshl_add_u64 v[210:211], v[210:211], 0, s[10:11]
	s_mov_b32 m0, s28
	ds_read_b128 v[162:165], v215 offset:49152
	ds_read_b128 v[166:169], v215 offset:50176
	ds_read_b128 v[170:173], v215 offset:51200
	ds_read_b128 v[174:177], v215 offset:52224
	ds_read_b128 v[194:197], v215 offset:53248
	ds_read_b128 v[198:201], v215 offset:54272
	ds_read_b128 v[202:205], v215 offset:55296
	ds_read_b128 v[206:209], v215 offset:56320
	global_load_lds_dwordx4 v[210:211], off
	s_add_i32 m0, s28, 0x2000
	s_add_u32 s26, s26, 0x40080
	v_lshl_add_u64 v[210:211], v[220:221], 0, s[10:11]
	s_addc_u32 s27, s27, 0
	s_add_i32 s28, s50, s37
	global_load_lds_dwordx4 v[210:211], off
	v_lshl_add_u64 v[210:211], s[26:27], 0, v[180:181]
	s_mov_b32 m0, s28
	s_nop 0
	global_load_lds_dwordx4 v[210:211], off
	v_lshl_add_u64 v[210:211], s[26:27], 0, v[184:185]
	s_add_i32 m0, s28, 0x2000
	s_nop 0
	global_load_lds_dwordx4 v[210:211], off
	v_lshl_add_u64 v[210:211], v[222:223], 0, s[10:11]
	s_mov_b32 m0, s43
	s_nop 0
	global_load_lds_dwordx4 v[210:211], off
	v_lshl_add_u64 v[210:211], v[224:225], 0, s[10:11]
	s_mov_b32 m0, s44
	s_nop 0
	global_load_lds_dwordx4 v[210:211], off
	s_waitcnt vmcnt(8)
	s_waitcnt lgkmcnt(0)
	s_barrier
	s_setprio 1
	s_waitcnt lgkmcnt(0)
	v_mfma_f32_16x16x32_bf16 v[62:65], v[130:133], v[162:165], v[62:65]
	v_mfma_f32_16x16x32_bf16 v[58:61], v[138:141], v[162:165], v[58:61]
	v_mfma_f32_16x16x32_bf16 v[46:49], v[130:133], v[170:173], v[46:49]
	v_mfma_f32_16x16x32_bf16 v[42:45], v[138:141], v[170:173], v[42:45]
	v_mfma_f32_16x16x32_bf16 v[30:33], v[130:133], v[194:197], v[30:33]
	v_mfma_f32_16x16x32_bf16 v[26:29], v[138:141], v[194:197], v[26:29]
	v_mfma_f32_16x16x32_bf16 v[14:17], v[130:133], v[202:205], v[14:17]
	v_mfma_f32_16x16x32_bf16 v[10:13], v[138:141], v[202:205], v[10:13]
	v_mfma_f32_16x16x32_bf16 v[62:65], v[134:137], v[166:169], v[62:65]
	v_mfma_f32_16x16x32_bf16 v[58:61], v[142:145], v[166:169], v[58:61]
	v_mfma_f32_16x16x32_bf16 v[46:49], v[134:137], v[174:177], v[46:49]
	v_mfma_f32_16x16x32_bf16 v[42:45], v[142:145], v[174:177], v[42:45]
	v_mfma_f32_16x16x32_bf16 v[30:33], v[134:137], v[198:201], v[30:33]
	v_mfma_f32_16x16x32_bf16 v[26:29], v[142:145], v[198:201], v[26:29]
	v_mfma_f32_16x16x32_bf16 v[14:17], v[134:137], v[206:209], v[14:17]
	v_mfma_f32_16x16x32_bf16 v[10:13], v[142:145], v[206:209], v[10:13]
	s_setprio 0
	s_setprio 1
	v_mfma_f32_16x16x32_bf16 v[54:57], v[146:149], v[162:165], v[54:57]
	v_mfma_f32_16x16x32_bf16 v[50:53], v[154:157], v[162:165], v[50:53]
	v_mfma_f32_16x16x32_bf16 v[38:41], v[146:149], v[170:173], v[38:41]
	v_mfma_f32_16x16x32_bf16 v[34:37], v[154:157], v[170:173], v[34:37]
	v_mfma_f32_16x16x32_bf16 v[22:25], v[146:149], v[194:197], v[22:25]
	v_mfma_f32_16x16x32_bf16 v[18:21], v[154:157], v[194:197], v[18:21]
	v_mfma_f32_16x16x32_bf16 v[6:9], v[146:149], v[202:205], v[6:9]
	v_mfma_f32_16x16x32_bf16 v[2:5], v[154:157], v[202:205], v[2:5]
	v_mfma_f32_16x16x32_bf16 v[54:57], v[150:153], v[166:169], v[54:57]
	v_mfma_f32_16x16x32_bf16 v[50:53], v[158:161], v[166:169], v[50:53]
	v_mfma_f32_16x16x32_bf16 v[38:41], v[150:153], v[174:177], v[38:41]
	v_mfma_f32_16x16x32_bf16 v[34:37], v[158:161], v[174:177], v[34:37]
	v_mfma_f32_16x16x32_bf16 v[22:25], v[150:153], v[198:201], v[22:25]
	v_mfma_f32_16x16x32_bf16 v[18:21], v[158:161], v[198:201], v[18:21]
	v_mfma_f32_16x16x32_bf16 v[6:9], v[150:153], v[206:209], v[6:9]
	v_mfma_f32_16x16x32_bf16 v[2:5], v[158:161], v[206:209], v[2:5]
	s_setprio 0
	s_barrier
	s_add_i32 s55, s55, 2
	s_add_u32 s24, s24, 0x100
	s_addc_u32 s25, s25, 0
	s_add_u32 s53, s53, 0x100
	s_addc_u32 s54, s54, 0
	s_cmp_gt_u32 s55, 13
	s_cbranch_scc0 .LBB0_2387
	v_lshl_add_u32 v198, s22, 8, v1
	v_lshl_or_b32 v194, s12, 8, v212
	v_ashrrev_i32_e32 v195, 31, v194
	v_ashrrev_i32_e32 v199, 31, v198
	v_lshl_add_u64 v[196:197], v[194:195], 2, s[62:63]
	v_lshlrev_b64 v[130:131], 12, v[198:199]
	v_lshl_add_u64 v[236:237], v[196:197], 0, v[130:131]
	global_load_dwordx4 v[220:223], v[236:237], off nt
	global_load_dwordx4 v[224:227], v[236:237], off offset:16 nt
	global_load_dwordx4 v[228:231], v[236:237], off offset:512 nt
	global_load_dwordx4 v[232:235], v[236:237], off offset:528 nt
	v_or_b32_e32 v208, 16, v198
	v_or_b32_e32 v204, 32, v198
	v_or_b32_e32 v200, 48, v198
	v_ashrrev_i32_e32 v209, 31, v208
	v_ashrrev_i32_e32 v205, 31, v204
	v_ashrrev_i32_e32 v201, 31, v200
	v_lshlrev_b64 v[130:131], 12, v[208:209]
	v_lshlrev_b64 v[132:133], 12, v[204:205]
	v_lshlrev_b64 v[134:135], 12, v[200:201]
	v_lshl_add_u64 v[210:211], v[196:197], 0, v[130:131]
	v_lshl_add_u64 v[206:207], v[196:197], 0, v[132:133]
	v_lshl_add_u64 v[202:203], v[196:197], 0, v[134:135]
	global_load_dwordx4 v[170:173], v[210:211], off offset:16 nt
	global_load_dwordx4 v[174:177], v[210:211], off nt
	global_load_dwordx4 v[162:165], v[210:211], off offset:528 nt
	global_load_dwordx4 v[166:169], v[210:211], off offset:512 nt
	global_load_dwordx4 v[154:157], v[206:207], off offset:16 nt
	global_load_dwordx4 v[158:161], v[206:207], off nt
	global_load_dwordx4 v[146:149], v[206:207], off offset:528 nt
	global_load_dwordx4 v[150:153], v[206:207], off offset:512 nt
	global_load_dwordx4 v[138:141], v[202:203], off offset:16 nt
	global_load_dwordx4 v[142:145], v[202:203], off nt
	global_load_dwordx4 v[130:133], v[202:203], off offset:528 nt
	global_load_dwordx4 v[134:137], v[202:203], off offset:512 nt
	v_and_b32_e32 v238, 64, v216
	v_xor_b32_e32 v219, 16, v216
	v_add_u32_e32 v241, 64, v238
	v_cmp_lt_i32_e32 vcc, v219, v241
	v_lshlrev_b64 v[238:239], 10, v[198:199]
	v_xor_b32_e32 v240, 32, v216
	v_cndmask_b32_e32 v219, v216, v219, vcc
	v_lshlrev_b32_e32 v219, 2, v219
	v_lshl_add_u64 v[238:239], v[238:239], 0, v[194:195]
	v_cmp_lt_i32_e32 vcc, v240, v241
	v_lshlrev_b64 v[238:239], 1, v[238:239]
	s_lshl_b32 s22, s12, 2
	v_cndmask_b32_e32 v242, v216, v240, vcc
	v_lshl_add_u64 v[240:241], s[2:3], 0, v[238:239]
	v_or_b32_e32 v238, 0x100, v238
	s_ashr_i32 s23, s22, 31
	s_waitcnt vmcnt(0)
	v_pk_add_f32 v[128:129], v[128:129], v[222:223]
	v_pk_add_f32 v[126:127], v[126:127], v[220:221]
	v_pk_add_f32 v[120:121], v[120:121], v[230:231]
	v_pk_add_f32 v[118:119], v[118:119], v[228:229]
	v_pk_add_f32 v[124:125], v[124:125], v[226:227]
	v_pk_add_f32 v[122:123], v[122:123], v[224:225]
	v_pk_add_f32 v[114:115], v[114:115], v[232:233]
	global_store_dwordx4 v[236:237], v[126:129], off nt
	global_store_dwordx4 v[236:237], v[122:125], off offset:16 nt
	v_cvt_pk_bf16_f32 v220, v126, v127
	v_cvt_pk_bf16_f32 v221, v128, v129
	v_mul_f32_e32 v224, v119, v119
	v_mul_f32_e32 v127, v127, v127
	v_mul_f32_e32 v129, v129, v129
	v_mul_f32_e32 v225, v121, v121
	v_pk_add_f32 v[116:117], v[116:117], v[234:235]
	v_cvt_pk_bf16_f32 v222, v122, v123
	v_cvt_pk_bf16_f32 v223, v124, v125
	v_mul_f32_e32 v123, v123, v123
	v_mul_f32_e32 v125, v125, v125
	v_mul_f32_e32 v226, v115, v115
	v_fmac_f32_e32 v127, v126, v126
	v_fmac_f32_e32 v129, v128, v128
	v_fmac_f32_e32 v224, v118, v118
	v_fmac_f32_e32 v225, v120, v120
	v_mul_f32_e32 v227, v117, v117
	v_fmac_f32_e32 v123, v122, v122
	v_fmac_f32_e32 v125, v124, v124
	v_fmac_f32_e32 v226, v114, v114
	v_add_f32_e32 v122, v127, v129
	v_add_f32_e32 v124, v224, v225
	v_fmac_f32_e32 v227, v116, v116
	v_add_f32_e32 v122, v122, v123
	v_add_f32_e32 v123, v124, v226
	v_add_f32_e32 v122, v125, v122
	v_add_f32_e32 v123, v227, v123
	v_add_f32_e32 v122, v122, v123
	ds_bpermute_b32 v123, v219, v122
	global_store_dwordx4 v[240:241], v[220:223], off nt
	global_store_dwordx4 v[236:237], v[118:121], off offset:512 nt
	global_store_dwordx4 v[236:237], v[114:117], off offset:528 nt
	v_lshlrev_b32_e32 v128, 2, v242
	v_cvt_pk_bf16_f32 v118, v118, v119
	v_cvt_pk_bf16_f32 v119, v120, v121
	v_cvt_pk_bf16_f32 v120, v114, v115
	v_cvt_pk_bf16_f32 v121, v116, v117
	s_waitcnt lgkmcnt(0)
	v_add_f32_e32 v114, v122, v123
	ds_bpermute_b32 v115, v128, v114
	v_lshl_add_u64 v[116:117], s[2:3], 0, v[238:239]
	global_store_dwordx4 v[116:117], v[118:121], off nt
	s_and_saveexec_b64 s[24:25], s[4:5]
	s_cbranch_execz .LBB0_2390
	s_waitcnt lgkmcnt(0)
	v_add_f32_e32 v116, v114, v115
	v_lshlrev_b64 v[114:115], 6, v[198:199]
	v_lshl_add_u64 v[114:115], s[8:9], 0, v[114:115]
	v_lshl_add_u64 v[114:115], s[22:23], 2, v[114:115]
	s_lshl_b32 s12, s42, 2
	v_lshl_add_u64 v[114:115], v[114:115], 0, s[12:13]
	global_store_dword v[114:115], v116, off
.LBB0_2390:
	s_or_b64 exec, exec, s[24:25]
	s_waitcnt lgkmcnt(0)
	v_lshlrev_b64 v[114:115], 10, v[208:209]
	v_pk_add_f32 v[112:113], v[112:113], v[176:177]
	v_pk_add_f32 v[110:111], v[110:111], v[174:175]
	v_lshl_add_u64 v[118:119], v[114:115], 0, v[194:195]
	v_pk_add_f32 v[108:109], v[108:109], v[172:173]
	v_pk_add_f32 v[106:107], v[106:107], v[170:171]
	global_store_dwordx4 v[210:211], v[110:113], off nt
	global_store_dwordx4 v[210:211], v[106:109], off offset:16 nt
	v_cvt_pk_bf16_f32 v114, v110, v111
	v_cvt_pk_bf16_f32 v115, v112, v113
	v_cvt_pk_bf16_f32 v116, v106, v107
	v_pk_add_f32 v[104:105], v[104:105], v[168:169]
	v_mul_f32_e32 v111, v111, v111
	v_fmac_f32_e32 v111, v110, v110
	v_mul_f32_e32 v110, v113, v113
	v_fmac_f32_e32 v110, v112, v112
	v_mul_f32_e32 v107, v107, v107
	v_add_f32_e32 v110, v111, v110
	v_fmac_f32_e32 v107, v106, v106
	v_add_f32_e32 v106, v110, v107
	v_mul_f32_e32 v107, v109, v109
	v_fmac_f32_e32 v107, v108, v108
	v_pk_add_f32 v[102:103], v[102:103], v[166:167]
	v_cvt_pk_bf16_f32 v117, v108, v109
	v_add_f32_e32 v106, v107, v106
	v_mul_f32_e32 v107, v103, v103
	v_mul_f32_e32 v108, v105, v105
	v_pk_add_f32 v[98:99], v[98:99], v[162:163]
	v_fmac_f32_e32 v107, v102, v102
	v_fmac_f32_e32 v108, v104, v104
	v_add_f32_e32 v107, v107, v108
	v_mul_f32_e32 v108, v99, v99
	v_pk_add_f32 v[100:101], v[100:101], v[164:165]
	v_fmac_f32_e32 v108, v98, v98
	v_add_f32_e32 v107, v107, v108
	v_mul_f32_e32 v108, v101, v101
	v_fmac_f32_e32 v108, v100, v100
	v_add_f32_e32 v107, v108, v107
	v_add_f32_e32 v106, v106, v107
	ds_bpermute_b32 v107, v219, v106
	v_lshlrev_b64 v[118:119], 1, v[118:119]
	v_lshl_add_u64 v[120:121], s[2:3], 0, v[118:119]
	global_store_dwordx4 v[120:121], v[114:117], off nt
	global_store_dwordx4 v[210:211], v[102:105], off offset:512 nt
	global_store_dwordx4 v[210:211], v[98:101], off offset:528 nt
	v_or_b32_e32 v118, 0x100, v118
	v_cvt_pk_bf16_f32 v102, v102, v103
	v_cvt_pk_bf16_f32 v103, v104, v105
	v_cvt_pk_bf16_f32 v104, v98, v99
	v_cvt_pk_bf16_f32 v105, v100, v101
	s_waitcnt lgkmcnt(0)
	v_add_f32_e32 v98, v106, v107
	ds_bpermute_b32 v99, v128, v98
	v_lshl_add_u64 v[100:101], s[2:3], 0, v[118:119]
	global_store_dwordx4 v[100:101], v[102:105], off nt
	s_and_saveexec_b64 s[24:25], s[4:5]
	s_cbranch_execz .LBB0_2392
	s_waitcnt lgkmcnt(0)
	v_add_f32_e32 v100, v98, v99
	v_lshlrev_b64 v[98:99], 6, v[208:209]
	v_lshl_add_u64 v[98:99], s[8:9], 0, v[98:99]
	v_lshl_add_u64 v[98:99], s[22:23], 2, v[98:99]
	s_lshl_b32 s12, s42, 2
	v_lshl_add_u64 v[98:99], v[98:99], 0, s[12:13]
	global_store_dword v[98:99], v100, off
.LBB0_2392:
	s_or_b64 exec, exec, s[24:25]
	s_waitcnt lgkmcnt(0)
	v_lshlrev_b64 v[98:99], 10, v[204:205]
	v_pk_add_f32 v[96:97], v[96:97], v[160:161]
	v_pk_add_f32 v[94:95], v[94:95], v[158:159]
	v_lshl_add_u64 v[102:103], v[98:99], 0, v[194:195]
	v_pk_add_f32 v[92:93], v[92:93], v[156:157]
	v_pk_add_f32 v[90:91], v[90:91], v[154:155]
	global_store_dwordx4 v[206:207], v[94:97], off nt
	global_store_dwordx4 v[206:207], v[90:93], off offset:16 nt
	v_cvt_pk_bf16_f32 v98, v94, v95
	v_cvt_pk_bf16_f32 v99, v96, v97
	v_cvt_pk_bf16_f32 v100, v90, v91
	v_pk_add_f32 v[88:89], v[88:89], v[152:153]
	v_mul_f32_e32 v95, v95, v95
	v_fmac_f32_e32 v95, v94, v94
	v_mul_f32_e32 v94, v97, v97
	v_fmac_f32_e32 v94, v96, v96
	v_mul_f32_e32 v91, v91, v91
	v_add_f32_e32 v94, v95, v94
	v_fmac_f32_e32 v91, v90, v90
	v_add_f32_e32 v90, v94, v91
	v_mul_f32_e32 v91, v93, v93
	v_fmac_f32_e32 v91, v92, v92
	v_pk_add_f32 v[86:87], v[86:87], v[150:151]
	v_cvt_pk_bf16_f32 v101, v92, v93
	v_add_f32_e32 v90, v91, v90
	v_mul_f32_e32 v91, v87, v87
	v_mul_f32_e32 v92, v89, v89
	v_pk_add_f32 v[82:83], v[82:83], v[146:147]
	v_fmac_f32_e32 v91, v86, v86
	v_fmac_f32_e32 v92, v88, v88
	v_add_f32_e32 v91, v91, v92
	v_mul_f32_e32 v92, v83, v83
	v_pk_add_f32 v[84:85], v[84:85], v[148:149]
	v_fmac_f32_e32 v92, v82, v82
	v_add_f32_e32 v91, v91, v92
	v_mul_f32_e32 v92, v85, v85
	v_fmac_f32_e32 v92, v84, v84
	v_add_f32_e32 v91, v92, v91
	v_add_f32_e32 v90, v90, v91
	ds_bpermute_b32 v91, v219, v90
	v_lshlrev_b64 v[102:103], 1, v[102:103]
	v_lshl_add_u64 v[104:105], s[2:3], 0, v[102:103]
	global_store_dwordx4 v[104:105], v[98:101], off nt
	global_store_dwordx4 v[206:207], v[86:89], off offset:512 nt
	global_store_dwordx4 v[206:207], v[82:85], off offset:528 nt
	v_or_b32_e32 v102, 0x100, v102
	v_cvt_pk_bf16_f32 v86, v86, v87
	v_cvt_pk_bf16_f32 v87, v88, v89
	v_cvt_pk_bf16_f32 v88, v82, v83
	v_cvt_pk_bf16_f32 v89, v84, v85
	s_waitcnt lgkmcnt(0)
	v_add_f32_e32 v82, v90, v91
	ds_bpermute_b32 v83, v128, v82
	v_lshl_add_u64 v[84:85], s[2:3], 0, v[102:103]
	global_store_dwordx4 v[84:85], v[86:89], off nt
	s_and_saveexec_b64 s[24:25], s[4:5]
	s_cbranch_execz .LBB0_2394
	s_waitcnt lgkmcnt(0)
	v_add_f32_e32 v84, v82, v83
	v_lshlrev_b64 v[82:83], 6, v[204:205]
	v_lshl_add_u64 v[82:83], s[8:9], 0, v[82:83]
	v_lshl_add_u64 v[82:83], s[22:23], 2, v[82:83]
	s_lshl_b32 s12, s42, 2
	v_lshl_add_u64 v[82:83], v[82:83], 0, s[12:13]
	global_store_dword v[82:83], v84, off
.LBB0_2394:
	s_or_b64 exec, exec, s[24:25]
	s_waitcnt lgkmcnt(0)
	v_lshlrev_b64 v[82:83], 10, v[200:201]
	v_pk_add_f32 v[80:81], v[80:81], v[144:145]
	v_pk_add_f32 v[78:79], v[78:79], v[142:143]
	v_lshl_add_u64 v[86:87], v[82:83], 0, v[194:195]
	v_pk_add_f32 v[76:77], v[76:77], v[140:141]
	v_pk_add_f32 v[74:75], v[74:75], v[138:139]
	global_store_dwordx4 v[202:203], v[78:81], off nt
	global_store_dwordx4 v[202:203], v[74:77], off offset:16 nt
	v_cvt_pk_bf16_f32 v82, v78, v79
	v_cvt_pk_bf16_f32 v83, v80, v81
	v_cvt_pk_bf16_f32 v84, v74, v75
	v_pk_add_f32 v[72:73], v[72:73], v[136:137]
	v_mul_f32_e32 v79, v79, v79
	v_fmac_f32_e32 v79, v78, v78
	v_mul_f32_e32 v78, v81, v81
	v_fmac_f32_e32 v78, v80, v80
	v_mul_f32_e32 v75, v75, v75
	v_add_f32_e32 v78, v79, v78
	v_fmac_f32_e32 v75, v74, v74
	v_add_f32_e32 v74, v78, v75
	v_mul_f32_e32 v75, v77, v77
	v_fmac_f32_e32 v75, v76, v76
	v_pk_add_f32 v[70:71], v[70:71], v[134:135]
	v_cvt_pk_bf16_f32 v85, v76, v77
	v_add_f32_e32 v74, v75, v74
	v_mul_f32_e32 v75, v71, v71
	v_mul_f32_e32 v76, v73, v73
	v_pk_add_f32 v[66:67], v[66:67], v[130:131]
	v_fmac_f32_e32 v75, v70, v70
	v_fmac_f32_e32 v76, v72, v72
	v_add_f32_e32 v75, v75, v76
	v_mul_f32_e32 v76, v67, v67
	v_pk_add_f32 v[68:69], v[68:69], v[132:133]
	v_fmac_f32_e32 v76, v66, v66
	v_add_f32_e32 v75, v75, v76
	v_mul_f32_e32 v76, v69, v69
	v_fmac_f32_e32 v76, v68, v68
	v_add_f32_e32 v75, v76, v75
	v_add_f32_e32 v74, v74, v75
	ds_bpermute_b32 v75, v219, v74
	v_lshlrev_b64 v[86:87], 1, v[86:87]
	v_lshl_add_u64 v[88:89], s[2:3], 0, v[86:87]
	global_store_dwordx4 v[88:89], v[82:85], off nt
	global_store_dwordx4 v[202:203], v[70:73], off offset:512 nt
	global_store_dwordx4 v[202:203], v[66:69], off offset:528 nt
	v_or_b32_e32 v86, 0x100, v86
	v_cvt_pk_bf16_f32 v70, v70, v71
	v_cvt_pk_bf16_f32 v71, v72, v73
	v_cvt_pk_bf16_f32 v72, v66, v67
	v_cvt_pk_bf16_f32 v73, v68, v69
	s_waitcnt lgkmcnt(0)
	v_add_f32_e32 v66, v74, v75
	ds_bpermute_b32 v67, v128, v66
	v_lshl_add_u64 v[68:69], s[2:3], 0, v[86:87]
	global_store_dwordx4 v[68:69], v[70:73], off nt
	s_and_saveexec_b64 s[24:25], s[4:5]
	s_cbranch_execz .LBB0_2396
	s_waitcnt lgkmcnt(0)
	v_add_f32_e32 v68, v66, v67
	v_lshlrev_b64 v[66:67], 6, v[200:201]
	v_lshl_add_u64 v[66:67], s[8:9], 0, v[66:67]
	v_lshl_add_u64 v[66:67], s[22:23], 2, v[66:67]
	s_lshl_b32 s12, s42, 2
	v_lshl_add_u64 v[66:67], v[66:67], 0, s[12:13]
	global_store_dword v[66:67], v68, off
.LBB0_2396:
	s_or_b64 exec, exec, s[24:25]
	v_add_u32_e32 v126, 0x80, v198
	v_ashrrev_i32_e32 v127, 31, v126
	s_waitcnt lgkmcnt(0)
	v_lshlrev_b64 v[66:67], 12, v[126:127]
	v_lshl_add_u64 v[146:147], v[196:197], 0, v[66:67]
	global_load_dwordx4 v[130:133], v[146:147], off nt
	global_load_dwordx4 v[134:137], v[146:147], off offset:16 nt
	global_load_dwordx4 v[138:141], v[146:147], off offset:512 nt
	global_load_dwordx4 v[142:145], v[146:147], off offset:528 nt
	v_add_u32_e32 v122, 0x90, v198
	v_add_u32_e32 v118, 0xa0, v198
	v_add_u32_e32 v114, 0xb0, v198
	v_ashrrev_i32_e32 v123, 31, v122
	v_ashrrev_i32_e32 v119, 31, v118
	v_ashrrev_i32_e32 v115, 31, v114
	v_lshlrev_b64 v[66:67], 12, v[122:123]
	v_lshlrev_b64 v[68:69], 12, v[118:119]
	v_lshlrev_b64 v[70:71], 12, v[114:115]
	v_lshl_add_u64 v[124:125], v[196:197], 0, v[66:67]
	v_lshl_add_u64 v[120:121], v[196:197], 0, v[68:69]
	v_lshl_add_u64 v[116:117], v[196:197], 0, v[70:71]
	global_load_dwordx4 v[106:109], v[124:125], off offset:16 nt
	global_load_dwordx4 v[110:113], v[124:125], off nt
	global_load_dwordx4 v[98:101], v[124:125], off offset:528 nt
	global_load_dwordx4 v[102:105], v[124:125], off offset:512 nt
	global_load_dwordx4 v[90:93], v[120:121], off offset:16 nt
	global_load_dwordx4 v[94:97], v[120:121], off nt
	global_load_dwordx4 v[82:85], v[120:121], off offset:528 nt
	global_load_dwordx4 v[86:89], v[120:121], off offset:512 nt
	global_load_dwordx4 v[74:77], v[116:117], off offset:16 nt
	global_load_dwordx4 v[78:81], v[116:117], off nt
	global_load_dwordx4 v[66:69], v[116:117], off offset:528 nt
	global_load_dwordx4 v[70:73], v[116:117], off offset:512 nt
	v_lshlrev_b64 v[148:149], 10, v[126:127]
	v_lshl_add_u64 v[148:149], v[148:149], 0, v[194:195]
	v_lshlrev_b64 v[148:149], 1, v[148:149]
	v_lshl_add_u64 v[150:151], s[2:3], 0, v[148:149]
	v_or_b32_e32 v148, 0x100, v148
	s_waitcnt vmcnt(15)
	v_pk_add_f32 v[64:65], v[64:65], v[132:133]
	v_pk_add_f32 v[62:63], v[62:63], v[130:131]
	s_waitcnt vmcnt(13)
	v_pk_add_f32 v[56:57], v[56:57], v[140:141]
	v_pk_add_f32 v[54:55], v[54:55], v[138:139]
	v_pk_add_f32 v[60:61], v[60:61], v[136:137]
	v_pk_add_f32 v[58:59], v[58:59], v[134:135]
	s_waitcnt vmcnt(12)
	v_pk_add_f32 v[50:51], v[50:51], v[142:143]
	global_store_dwordx4 v[146:147], v[62:65], off nt
	global_store_dwordx4 v[146:147], v[58:61], off offset:16 nt
	v_cvt_pk_bf16_f32 v130, v62, v63
	v_cvt_pk_bf16_f32 v131, v64, v65
	v_mul_f32_e32 v129, v55, v55
	v_mul_f32_e32 v63, v63, v63
	v_mul_f32_e32 v65, v65, v65
	v_mul_f32_e32 v134, v57, v57
	v_pk_add_f32 v[52:53], v[52:53], v[144:145]
	v_cvt_pk_bf16_f32 v132, v58, v59
	v_cvt_pk_bf16_f32 v133, v60, v61
	v_mul_f32_e32 v59, v59, v59
	v_mul_f32_e32 v61, v61, v61
	v_mul_f32_e32 v135, v51, v51
	v_fmac_f32_e32 v63, v62, v62
	v_fmac_f32_e32 v65, v64, v64
	v_fmac_f32_e32 v129, v54, v54
	v_fmac_f32_e32 v134, v56, v56
	v_mul_f32_e32 v136, v53, v53
	v_fmac_f32_e32 v59, v58, v58
	v_fmac_f32_e32 v61, v60, v60
	v_fmac_f32_e32 v135, v50, v50
	v_add_f32_e32 v58, v63, v65
	v_add_f32_e32 v60, v129, v134
	v_fmac_f32_e32 v136, v52, v52
	v_add_f32_e32 v58, v58, v59
	v_add_f32_e32 v59, v60, v135
	v_add_f32_e32 v58, v61, v58
	v_add_f32_e32 v59, v136, v59
	v_add_f32_e32 v58, v58, v59
	ds_bpermute_b32 v59, v219, v58
	global_store_dwordx4 v[150:151], v[130:133], off nt
	global_store_dwordx4 v[146:147], v[54:57], off offset:512 nt
	global_store_dwordx4 v[146:147], v[50:53], off offset:528 nt
	s_nop 0
	v_cvt_pk_bf16_f32 v54, v54, v55
	v_cvt_pk_bf16_f32 v55, v56, v57
	v_cvt_pk_bf16_f32 v56, v50, v51
	v_cvt_pk_bf16_f32 v57, v52, v53
	s_waitcnt lgkmcnt(0)
	v_add_f32_e32 v50, v58, v59
	ds_bpermute_b32 v51, v128, v50
	v_lshl_add_u64 v[52:53], s[2:3], 0, v[148:149]
	global_store_dwordx4 v[52:53], v[54:57], off nt
	s_and_saveexec_b64 s[24:25], s[4:5]
	s_cbranch_execz .LBB0_2398
	s_waitcnt lgkmcnt(0)
	v_add_f32_e32 v52, v50, v51
	v_lshlrev_b64 v[50:51], 6, v[126:127]
	v_lshl_add_u64 v[50:51], s[8:9], 0, v[50:51]
	v_lshl_add_u64 v[50:51], s[22:23], 2, v[50:51]
	s_lshl_b32 s12, s42, 2
	v_lshl_add_u64 v[50:51], v[50:51], 0, s[12:13]
	global_store_dword v[50:51], v52, off
.LBB0_2398:
	s_or_b64 exec, exec, s[24:25]
	s_waitcnt lgkmcnt(0)
	v_lshlrev_b64 v[50:51], 10, v[122:123]
	s_waitcnt vmcnt(16)
	v_pk_add_f32 v[48:49], v[48:49], v[112:113]
	v_pk_add_f32 v[46:47], v[46:47], v[110:111]
	v_lshl_add_u64 v[54:55], v[50:51], 0, v[194:195]
	v_pk_add_f32 v[44:45], v[44:45], v[108:109]
	v_pk_add_f32 v[42:43], v[42:43], v[106:107]
	global_store_dwordx4 v[124:125], v[46:49], off nt
	global_store_dwordx4 v[124:125], v[42:45], off offset:16 nt
	v_cvt_pk_bf16_f32 v50, v46, v47
	v_cvt_pk_bf16_f32 v51, v48, v49
	v_cvt_pk_bf16_f32 v52, v42, v43
	s_waitcnt vmcnt(16)
	v_pk_add_f32 v[40:41], v[40:41], v[104:105]
	v_mul_f32_e32 v47, v47, v47
	v_fmac_f32_e32 v47, v46, v46
	v_mul_f32_e32 v46, v49, v49
	v_fmac_f32_e32 v46, v48, v48
	v_mul_f32_e32 v43, v43, v43
	v_add_f32_e32 v46, v47, v46
	v_fmac_f32_e32 v43, v42, v42
	v_add_f32_e32 v42, v46, v43
	v_mul_f32_e32 v43, v45, v45
	v_fmac_f32_e32 v43, v44, v44
	v_pk_add_f32 v[38:39], v[38:39], v[102:103]
	v_cvt_pk_bf16_f32 v53, v44, v45
	v_add_f32_e32 v42, v43, v42
	v_mul_f32_e32 v43, v39, v39
	v_mul_f32_e32 v44, v41, v41
	v_pk_add_f32 v[34:35], v[34:35], v[98:99]
	v_fmac_f32_e32 v43, v38, v38
	v_fmac_f32_e32 v44, v40, v40
	v_add_f32_e32 v43, v43, v44
	v_mul_f32_e32 v44, v35, v35
	v_pk_add_f32 v[36:37], v[36:37], v[100:101]
	v_fmac_f32_e32 v44, v34, v34
	v_add_f32_e32 v43, v43, v44
	v_mul_f32_e32 v44, v37, v37
	v_fmac_f32_e32 v44, v36, v36
	v_add_f32_e32 v43, v44, v43
	v_add_f32_e32 v42, v42, v43
	ds_bpermute_b32 v43, v219, v42
	v_lshlrev_b64 v[54:55], 1, v[54:55]
	v_lshl_add_u64 v[56:57], s[2:3], 0, v[54:55]
	global_store_dwordx4 v[56:57], v[50:53], off nt
	global_store_dwordx4 v[124:125], v[38:41], off offset:512 nt
	global_store_dwordx4 v[124:125], v[34:37], off offset:528 nt
	v_or_b32_e32 v54, 0x100, v54
	v_cvt_pk_bf16_f32 v38, v38, v39
	v_cvt_pk_bf16_f32 v39, v40, v41
	v_cvt_pk_bf16_f32 v40, v34, v35
	v_cvt_pk_bf16_f32 v41, v36, v37
	s_waitcnt lgkmcnt(0)
	v_add_f32_e32 v34, v42, v43
	ds_bpermute_b32 v35, v128, v34
	v_lshl_add_u64 v[36:37], s[2:3], 0, v[54:55]
	global_store_dwordx4 v[36:37], v[38:41], off nt
	s_and_saveexec_b64 s[24:25], s[4:5]
	s_cbranch_execz .LBB0_2400
	s_waitcnt lgkmcnt(0)
	v_add_f32_e32 v36, v34, v35
	v_lshlrev_b64 v[34:35], 6, v[122:123]
	v_lshl_add_u64 v[34:35], s[8:9], 0, v[34:35]
	v_lshl_add_u64 v[34:35], s[22:23], 2, v[34:35]
	s_lshl_b32 s12, s42, 2
	v_lshl_add_u64 v[34:35], v[34:35], 0, s[12:13]
	global_store_dword v[34:35], v36, off
.LBB0_2400:
	s_or_b64 exec, exec, s[24:25]
	s_waitcnt lgkmcnt(0)
	v_lshlrev_b64 v[34:35], 10, v[118:119]
	s_waitcnt vmcnt(18)
	v_pk_add_f32 v[32:33], v[32:33], v[96:97]
	v_pk_add_f32 v[30:31], v[30:31], v[94:95]
	v_lshl_add_u64 v[38:39], v[34:35], 0, v[194:195]
	v_pk_add_f32 v[28:29], v[28:29], v[92:93]
	v_pk_add_f32 v[26:27], v[26:27], v[90:91]
	global_store_dwordx4 v[120:121], v[30:33], off nt
	global_store_dwordx4 v[120:121], v[26:29], off offset:16 nt
	v_cvt_pk_bf16_f32 v34, v30, v31
	v_cvt_pk_bf16_f32 v35, v32, v33
	v_cvt_pk_bf16_f32 v36, v26, v27
	s_waitcnt vmcnt(18)
	v_pk_add_f32 v[24:25], v[24:25], v[88:89]
	v_mul_f32_e32 v31, v31, v31
	v_fmac_f32_e32 v31, v30, v30
	v_mul_f32_e32 v30, v33, v33
	v_fmac_f32_e32 v30, v32, v32
	v_mul_f32_e32 v27, v27, v27
	v_add_f32_e32 v30, v31, v30
	v_fmac_f32_e32 v27, v26, v26
	v_add_f32_e32 v26, v30, v27
	v_mul_f32_e32 v27, v29, v29
	v_fmac_f32_e32 v27, v28, v28
	v_pk_add_f32 v[22:23], v[22:23], v[86:87]
	v_cvt_pk_bf16_f32 v37, v28, v29
	v_add_f32_e32 v26, v27, v26
	v_mul_f32_e32 v27, v23, v23
	v_mul_f32_e32 v28, v25, v25
	v_pk_add_f32 v[18:19], v[18:19], v[82:83]
	v_fmac_f32_e32 v27, v22, v22
	v_fmac_f32_e32 v28, v24, v24
	v_add_f32_e32 v27, v27, v28
	v_mul_f32_e32 v28, v19, v19
	v_pk_add_f32 v[20:21], v[20:21], v[84:85]
	v_fmac_f32_e32 v28, v18, v18
	v_add_f32_e32 v27, v27, v28
	v_mul_f32_e32 v28, v21, v21
	v_fmac_f32_e32 v28, v20, v20
	v_add_f32_e32 v27, v28, v27
	v_add_f32_e32 v26, v26, v27
	ds_bpermute_b32 v27, v219, v26
	v_lshlrev_b64 v[38:39], 1, v[38:39]
	v_lshl_add_u64 v[40:41], s[2:3], 0, v[38:39]
	global_store_dwordx4 v[40:41], v[34:37], off nt
	global_store_dwordx4 v[120:121], v[22:25], off offset:512 nt
	global_store_dwordx4 v[120:121], v[18:21], off offset:528 nt
	v_or_b32_e32 v38, 0x100, v38
	v_cvt_pk_bf16_f32 v22, v22, v23
	v_cvt_pk_bf16_f32 v23, v24, v25
	v_cvt_pk_bf16_f32 v24, v18, v19
	v_cvt_pk_bf16_f32 v25, v20, v21
	s_waitcnt lgkmcnt(0)
	v_add_f32_e32 v18, v26, v27
	ds_bpermute_b32 v19, v128, v18
	v_lshl_add_u64 v[20:21], s[2:3], 0, v[38:39]
	global_store_dwordx4 v[20:21], v[22:25], off nt
	s_and_saveexec_b64 s[24:25], s[4:5]
	s_cbranch_execz .LBB0_2402
	s_waitcnt lgkmcnt(0)
	v_add_f32_e32 v20, v18, v19
	v_lshlrev_b64 v[18:19], 6, v[118:119]
	v_lshl_add_u64 v[18:19], s[8:9], 0, v[18:19]
	v_lshl_add_u64 v[18:19], s[22:23], 2, v[18:19]
	s_lshl_b32 s12, s42, 2
	v_lshl_add_u64 v[18:19], v[18:19], 0, s[12:13]
	global_store_dword v[18:19], v20, off
.LBB0_2402:
	s_or_b64 exec, exec, s[24:25]
	s_waitcnt lgkmcnt(0)
	v_lshlrev_b64 v[18:19], 10, v[114:115]
	s_waitcnt vmcnt(20)
	v_pk_add_f32 v[16:17], v[16:17], v[80:81]
	v_pk_add_f32 v[14:15], v[14:15], v[78:79]
	v_lshl_add_u64 v[22:23], v[18:19], 0, v[194:195]
	v_pk_add_f32 v[12:13], v[12:13], v[76:77]
	v_pk_add_f32 v[10:11], v[10:11], v[74:75]
	global_store_dwordx4 v[116:117], v[14:17], off nt
	global_store_dwordx4 v[116:117], v[10:13], off offset:16 nt
	v_cvt_pk_bf16_f32 v18, v14, v15
	v_cvt_pk_bf16_f32 v19, v16, v17
	v_cvt_pk_bf16_f32 v20, v10, v11
	s_waitcnt vmcnt(20)
	v_pk_add_f32 v[8:9], v[8:9], v[72:73]
	v_mul_f32_e32 v15, v15, v15
	v_fmac_f32_e32 v15, v14, v14
	v_mul_f32_e32 v14, v17, v17
	v_fmac_f32_e32 v14, v16, v16
	v_mul_f32_e32 v11, v11, v11
	v_add_f32_e32 v14, v15, v14
	v_fmac_f32_e32 v11, v10, v10
	v_add_f32_e32 v10, v14, v11
	v_mul_f32_e32 v11, v13, v13
	v_fmac_f32_e32 v11, v12, v12
	v_pk_add_f32 v[6:7], v[6:7], v[70:71]
	v_cvt_pk_bf16_f32 v21, v12, v13
	v_add_f32_e32 v10, v11, v10
	v_mul_f32_e32 v11, v7, v7
	v_mul_f32_e32 v12, v9, v9
	v_pk_add_f32 v[2:3], v[2:3], v[66:67]
	v_fmac_f32_e32 v11, v6, v6
	v_fmac_f32_e32 v12, v8, v8
	v_add_f32_e32 v11, v11, v12
	v_mul_f32_e32 v12, v3, v3
	v_pk_add_f32 v[4:5], v[4:5], v[68:69]
	v_fmac_f32_e32 v12, v2, v2
	v_add_f32_e32 v11, v11, v12
	v_mul_f32_e32 v12, v5, v5
	v_fmac_f32_e32 v12, v4, v4
	v_add_f32_e32 v11, v12, v11
	v_add_f32_e32 v10, v10, v11
	ds_bpermute_b32 v11, v219, v10
	v_lshlrev_b64 v[22:23], 1, v[22:23]
	v_lshl_add_u64 v[24:25], s[2:3], 0, v[22:23]
	global_store_dwordx4 v[24:25], v[18:21], off nt
	global_store_dwordx4 v[116:117], v[6:9], off offset:512 nt
	global_store_dwordx4 v[116:117], v[2:5], off offset:528 nt
	v_or_b32_e32 v22, 0x100, v22
	v_cvt_pk_bf16_f32 v6, v6, v7
	v_cvt_pk_bf16_f32 v7, v8, v9
	v_cvt_pk_bf16_f32 v8, v2, v3
	v_cvt_pk_bf16_f32 v9, v4, v5
	s_waitcnt lgkmcnt(0)
	v_add_f32_e32 v2, v10, v11
	ds_bpermute_b32 v3, v128, v2
	v_lshl_add_u64 v[4:5], s[2:3], 0, v[22:23]
	global_store_dwordx4 v[4:5], v[6:9], off nt
	s_and_saveexec_b64 s[24:25], s[4:5]
	s_cbranch_execz .LBB0_2379
	s_waitcnt lgkmcnt(0)
	v_add_f32_e32 v4, v2, v3
	v_lshlrev_b64 v[2:3], 6, v[114:115]
	v_lshl_add_u64 v[2:3], s[8:9], 0, v[2:3]
	v_lshl_add_u64 v[2:3], s[22:23], 2, v[2:3]
	s_lshl_b32 s12, s42, 2
	v_lshl_add_u64 v[2:3], v[2:3], 0, s[12:13]
	global_store_dword v[2:3], v4, off
	s_branch .LBB0_2379

.LBB0_2471:
	ds_read_b128 v[130:133], v213
	ds_read_b128 v[134:137], v213 offset:1024
	ds_read_b128 v[138:141], v213 offset:2048
	ds_read_b128 v[142:145], v213 offset:3072
	ds_read_b128 v[146:149], v214
	ds_read_b128 v[150:153], v214 offset:1024
	ds_read_b128 v[154:157], v214 offset:2048
	ds_read_b128 v[158:161], v214 offset:3072
	s_add_u32 s20, s18, 0xfff50080
	s_addc_u32 s21, s19, -1
	s_cmp_eq_u32 s51, 40
	s_cselect_b32 s23, s9, s21
	s_cselect_b32 s22, s8, s20
	s_cselect_b32 s21, s11, s50
	s_cselect_b32 s20, s10, s49
	v_lshl_add_u64 v[210:211], s[18:19], 0, v[186:187]
	s_add_i32 m0, s31, 0xc000
	ds_read_b128 v[162:165], v215
	ds_read_b128 v[166:169], v215 offset:1024
	ds_read_b128 v[170:173], v215 offset:2048
	ds_read_b128 v[174:177], v215 offset:3072
	ds_read_b128 v[194:197], v215 offset:4096
	ds_read_b128 v[198:201], v215 offset:5120
	ds_read_b128 v[202:205], v215 offset:6144
	ds_read_b128 v[206:209], v215 offset:7168
	global_load_lds_dwordx4 v[210:211], off
	v_lshl_add_u64 v[210:211], s[18:19], 0, v[188:189]
	s_add_i32 m0, s31, 0xe000
	s_nop 0
	global_load_lds_dwordx4 v[210:211], off
	s_waitcnt vmcnt(8)
	s_waitcnt lgkmcnt(0)
	s_barrier
	s_setprio 1
	s_waitcnt lgkmcnt(0)
	v_mfma_f32_16x16x32_bf16 v[126:129], v[130:133], v[162:165], v[126:129]
	v_mfma_f32_16x16x32_bf16 v[122:125], v[138:141], v[162:165], v[122:125]
	v_mfma_f32_16x16x32_bf16 v[110:113], v[130:133], v[170:173], v[110:113]
	v_mfma_f32_16x16x32_bf16 v[106:109], v[138:141], v[170:173], v[106:109]
	v_mfma_f32_16x16x32_bf16 v[94:97], v[130:133], v[194:197], v[94:97]
	v_mfma_f32_16x16x32_bf16 v[90:93], v[138:141], v[194:197], v[90:93]
	v_mfma_f32_16x16x32_bf16 v[78:81], v[130:133], v[202:205], v[78:81]
	v_mfma_f32_16x16x32_bf16 v[74:77], v[138:141], v[202:205], v[74:77]
	v_mfma_f32_16x16x32_bf16 v[126:129], v[134:137], v[166:169], v[126:129]
	v_mfma_f32_16x16x32_bf16 v[122:125], v[142:145], v[166:169], v[122:125]
	v_mfma_f32_16x16x32_bf16 v[110:113], v[134:137], v[174:177], v[110:113]
	v_mfma_f32_16x16x32_bf16 v[106:109], v[142:145], v[174:177], v[106:109]
	v_mfma_f32_16x16x32_bf16 v[94:97], v[134:137], v[198:201], v[94:97]
	v_mfma_f32_16x16x32_bf16 v[90:93], v[142:145], v[198:201], v[90:93]
	v_mfma_f32_16x16x32_bf16 v[78:81], v[134:137], v[206:209], v[78:81]
	v_mfma_f32_16x16x32_bf16 v[74:77], v[142:145], v[206:209], v[74:77]
	s_setprio 0
	s_setprio 1
	v_mfma_f32_16x16x32_bf16 v[118:121], v[146:149], v[162:165], v[118:121]
	v_mfma_f32_16x16x32_bf16 v[114:117], v[154:157], v[162:165], v[114:117]
	v_mfma_f32_16x16x32_bf16 v[102:105], v[146:149], v[170:173], v[102:105]
	v_mfma_f32_16x16x32_bf16 v[98:101], v[154:157], v[170:173], v[98:101]
	v_mfma_f32_16x16x32_bf16 v[86:89], v[146:149], v[194:197], v[86:89]
	v_mfma_f32_16x16x32_bf16 v[82:85], v[154:157], v[194:197], v[82:85]
	v_mfma_f32_16x16x32_bf16 v[70:73], v[146:149], v[202:205], v[70:73]
	v_mfma_f32_16x16x32_bf16 v[66:69], v[154:157], v[202:205], v[66:69]
	v_mfma_f32_16x16x32_bf16 v[118:121], v[150:153], v[166:169], v[118:121]
	v_mfma_f32_16x16x32_bf16 v[114:117], v[158:161], v[166:169], v[114:117]
	v_mfma_f32_16x16x32_bf16 v[102:105], v[150:153], v[174:177], v[102:105]
	v_mfma_f32_16x16x32_bf16 v[98:101], v[158:161], v[174:177], v[98:101]
	v_mfma_f32_16x16x32_bf16 v[86:89], v[150:153], v[198:201], v[86:89]
	v_mfma_f32_16x16x32_bf16 v[82:85], v[158:161], v[198:201], v[82:85]
	v_mfma_f32_16x16x32_bf16 v[70:73], v[150:153], v[206:209], v[70:73]
	v_mfma_f32_16x16x32_bf16 v[66:69], v[158:161], v[206:209], v[66:69]
	s_setprio 0
	s_barrier
	s_add_i32 s52, s41, s30
	v_lshl_add_u64 v[210:211], s[20:21], 0, v[180:181]
	s_mov_b32 m0, s52
	ds_read_b128 v[162:165], v215 offset:16384
	ds_read_b128 v[166:169], v215 offset:17408
	ds_read_b128 v[170:173], v215 offset:18432
	ds_read_b128 v[174:177], v215 offset:19456
	ds_read_b128 v[194:197], v215 offset:20480
	ds_read_b128 v[198:201], v215 offset:21504
	ds_read_b128 v[202:205], v215 offset:22528
	ds_read_b128 v[206:209], v215 offset:23552
	global_load_lds_dwordx4 v[210:211], off
	s_add_i32 m0, s52, 0x2000
	s_add_u32 s52, s20, 0xb0000
	v_lshl_add_u64 v[220:221], s[20:21], 0, v[184:185]
	s_addc_u32 s53, s21, 0
	s_add_i32 s54, s42, s30
	global_load_lds_dwordx4 v[220:221], off
	v_lshl_add_u64 v[222:223], s[52:53], 0, v[180:181]
	s_mov_b32 m0, s54
	v_lshl_add_u64 v[224:225], s[22:23], 0, v[182:183]
	global_load_lds_dwordx4 v[222:223], off
	v_lshl_add_u64 v[222:223], s[52:53], 0, v[184:185]
	s_add_i32 m0, s54, 0x2000
	s_nop 0
	global_load_lds_dwordx4 v[222:223], off
	v_lshl_add_u64 v[222:223], s[22:23], 0, v[178:179]
	s_mov_b32 m0, s31
	s_nop 0
	global_load_lds_dwordx4 v[222:223], off
	s_mov_b32 m0, s33
	s_nop 0
	global_load_lds_dwordx4 v[224:225], off
	s_waitcnt vmcnt(8)
	s_waitcnt lgkmcnt(0)
	s_barrier
	s_setprio 1
	s_waitcnt lgkmcnt(0)
	v_mfma_f32_16x16x32_bf16 v[62:65], v[130:133], v[162:165], v[62:65]
	v_mfma_f32_16x16x32_bf16 v[58:61], v[138:141], v[162:165], v[58:61]
	v_mfma_f32_16x16x32_bf16 v[46:49], v[130:133], v[170:173], v[46:49]
	v_mfma_f32_16x16x32_bf16 v[42:45], v[138:141], v[170:173], v[42:45]
	v_mfma_f32_16x16x32_bf16 v[30:33], v[130:133], v[194:197], v[30:33]
	v_mfma_f32_16x16x32_bf16 v[26:29], v[138:141], v[194:197], v[26:29]
	v_mfma_f32_16x16x32_bf16 v[14:17], v[130:133], v[202:205], v[14:17]
	v_mfma_f32_16x16x32_bf16 v[10:13], v[138:141], v[202:205], v[10:13]
	v_mfma_f32_16x16x32_bf16 v[62:65], v[134:137], v[166:169], v[62:65]
	v_mfma_f32_16x16x32_bf16 v[58:61], v[142:145], v[166:169], v[58:61]
	v_mfma_f32_16x16x32_bf16 v[46:49], v[134:137], v[174:177], v[46:49]
	v_mfma_f32_16x16x32_bf16 v[42:45], v[142:145], v[174:177], v[42:45]
	v_mfma_f32_16x16x32_bf16 v[30:33], v[134:137], v[198:201], v[30:33]
	v_mfma_f32_16x16x32_bf16 v[26:29], v[142:145], v[198:201], v[26:29]
	v_mfma_f32_16x16x32_bf16 v[14:17], v[134:137], v[206:209], v[14:17]
	v_mfma_f32_16x16x32_bf16 v[10:13], v[142:145], v[206:209], v[10:13]
	s_setprio 0
	s_setprio 1
	v_mfma_f32_16x16x32_bf16 v[54:57], v[146:149], v[162:165], v[54:57]
	v_mfma_f32_16x16x32_bf16 v[50:53], v[154:157], v[162:165], v[50:53]
	v_mfma_f32_16x16x32_bf16 v[38:41], v[146:149], v[170:173], v[38:41]
	v_mfma_f32_16x16x32_bf16 v[34:37], v[154:157], v[170:173], v[34:37]
	v_mfma_f32_16x16x32_bf16 v[22:25], v[146:149], v[194:197], v[22:25]
	v_mfma_f32_16x16x32_bf16 v[18:21], v[154:157], v[194:197], v[18:21]
	v_mfma_f32_16x16x32_bf16 v[6:9], v[146:149], v[202:205], v[6:9]
	v_mfma_f32_16x16x32_bf16 v[2:5], v[154:157], v[202:205], v[2:5]
	v_mfma_f32_16x16x32_bf16 v[54:57], v[150:153], v[166:169], v[54:57]
	v_mfma_f32_16x16x32_bf16 v[50:53], v[158:161], v[166:169], v[50:53]
	v_mfma_f32_16x16x32_bf16 v[38:41], v[150:153], v[174:177], v[38:41]
	v_mfma_f32_16x16x32_bf16 v[34:37], v[158:161], v[174:177], v[34:37]
	v_mfma_f32_16x16x32_bf16 v[22:25], v[150:153], v[198:201], v[22:25]
	v_mfma_f32_16x16x32_bf16 v[18:21], v[158:161], v[198:201], v[18:21]
	v_mfma_f32_16x16x32_bf16 v[6:9], v[150:153], v[206:209], v[6:9]
	v_mfma_f32_16x16x32_bf16 v[2:5], v[158:161], v[206:209], v[2:5]
	s_setprio 0
	s_barrier
	ds_read_b128 v[130:133], v217
	ds_read_b128 v[134:137], v217 offset:1024
	ds_read_b128 v[138:141], v217 offset:2048
	ds_read_b128 v[142:145], v217 offset:3072
	ds_read_b128 v[146:149], v218
	ds_read_b128 v[150:153], v218 offset:1024
	ds_read_b128 v[154:157], v218 offset:2048
	ds_read_b128 v[158:161], v218 offset:3072
	s_add_u32 s22, s22, 0xb0000
	s_addc_u32 s23, s23, 0
	s_mov_b32 m0, s34
	v_lshl_add_u64 v[226:227], s[22:23], 0, v[178:179]
	ds_read_b128 v[162:165], v215 offset:32768
	ds_read_b128 v[166:169], v215 offset:33792
	ds_read_b128 v[170:173], v215 offset:34816
	ds_read_b128 v[174:177], v215 offset:35840
	ds_read_b128 v[194:197], v215 offset:36864
	ds_read_b128 v[198:201], v215 offset:37888
	ds_read_b128 v[202:205], v215 offset:38912
	ds_read_b128 v[206:209], v215 offset:39936
	global_load_lds_dwordx4 v[226:227], off
	v_lshl_add_u64 v[226:227], s[22:23], 0, v[182:183]
	s_mov_b32 m0, s35
	s_nop 0
	global_load_lds_dwordx4 v[226:227], off
	s_waitcnt vmcnt(8)
	s_waitcnt lgkmcnt(0)
	s_barrier
	s_setprio 1
	s_waitcnt lgkmcnt(0)
	v_mfma_f32_16x16x32_bf16 v[126:129], v[130:133], v[162:165], v[126:129]
	v_mfma_f32_16x16x32_bf16 v[122:125], v[138:141], v[162:165], v[122:125]
	v_mfma_f32_16x16x32_bf16 v[110:113], v[130:133], v[170:173], v[110:113]
	v_mfma_f32_16x16x32_bf16 v[106:109], v[138:141], v[170:173], v[106:109]
	v_mfma_f32_16x16x32_bf16 v[94:97], v[130:133], v[194:197], v[94:97]
	v_mfma_f32_16x16x32_bf16 v[90:93], v[138:141], v[194:197], v[90:93]
	v_mfma_f32_16x16x32_bf16 v[78:81], v[130:133], v[202:205], v[78:81]
	v_mfma_f32_16x16x32_bf16 v[74:77], v[138:141], v[202:205], v[74:77]
	v_mfma_f32_16x16x32_bf16 v[126:129], v[134:137], v[166:169], v[126:129]
	v_mfma_f32_16x16x32_bf16 v[122:125], v[142:145], v[166:169], v[122:125]
	v_mfma_f32_16x16x32_bf16 v[110:113], v[134:137], v[174:177], v[110:113]
	v_mfma_f32_16x16x32_bf16 v[106:109], v[142:145], v[174:177], v[106:109]
	v_mfma_f32_16x16x32_bf16 v[94:97], v[134:137], v[198:201], v[94:97]
	v_mfma_f32_16x16x32_bf16 v[90:93], v[142:145], v[198:201], v[90:93]
	v_mfma_f32_16x16x32_bf16 v[78:81], v[134:137], v[206:209], v[78:81]
	v_mfma_f32_16x16x32_bf16 v[74:77], v[142:145], v[206:209], v[74:77]
	s_setprio 0
	s_setprio 1
	v_mfma_f32_16x16x32_bf16 v[118:121], v[146:149], v[162:165], v[118:121]
	v_mfma_f32_16x16x32_bf16 v[114:117], v[154:157], v[162:165], v[114:117]
	v_mfma_f32_16x16x32_bf16 v[102:105], v[146:149], v[170:173], v[102:105]
	v_mfma_f32_16x16x32_bf16 v[98:101], v[154:157], v[170:173], v[98:101]
	v_mfma_f32_16x16x32_bf16 v[86:89], v[146:149], v[194:197], v[86:89]
	v_mfma_f32_16x16x32_bf16 v[82:85], v[154:157], v[194:197], v[82:85]
	v_mfma_f32_16x16x32_bf16 v[70:73], v[146:149], v[202:205], v[70:73]
	v_mfma_f32_16x16x32_bf16 v[66:69], v[154:157], v[202:205], v[66:69]
	v_mfma_f32_16x16x32_bf16 v[118:121], v[150:153], v[166:169], v[118:121]
	v_mfma_f32_16x16x32_bf16 v[114:117], v[158:161], v[166:169], v[114:117]
	v_mfma_f32_16x16x32_bf16 v[102:105], v[150:153], v[174:177], v[102:105]
	v_mfma_f32_16x16x32_bf16 v[98:101], v[158:161], v[174:177], v[98:101]
	v_mfma_f32_16x16x32_bf16 v[86:89], v[150:153], v[198:201], v[86:89]
	v_mfma_f32_16x16x32_bf16 v[82:85], v[158:161], v[198:201], v[82:85]
	v_mfma_f32_16x16x32_bf16 v[70:73], v[150:153], v[206:209], v[70:73]
	v_mfma_f32_16x16x32_bf16 v[66:69], v[158:161], v[206:209], v[66:69]
	s_setprio 0
	s_barrier
	s_add_i32 s22, s43, s30
	v_lshl_add_u64 v[210:211], v[210:211], 0, s[14:15]
	s_mov_b32 m0, s22
	ds_read_b128 v[162:165], v215 offset:49152
	ds_read_b128 v[166:169], v215 offset:50176
	ds_read_b128 v[170:173], v215 offset:51200
	ds_read_b128 v[174:177], v215 offset:52224
	ds_read_b128 v[194:197], v215 offset:53248
	ds_read_b128 v[198:201], v215 offset:54272
	ds_read_b128 v[202:205], v215 offset:55296
	ds_read_b128 v[206:209], v215 offset:56320
	global_load_lds_dwordx4 v[210:211], off
	s_add_i32 m0, s22, 0x2000
	s_add_u32 s20, s20, 0xb0080
	v_lshl_add_u64 v[210:211], v[220:221], 0, s[14:15]
	s_addc_u32 s21, s21, 0
	s_add_i32 s22, s44, s30
	global_load_lds_dwordx4 v[210:211], off
	v_lshl_add_u64 v[210:211], s[20:21], 0, v[180:181]
	s_mov_b32 m0, s22
	s_nop 0
	global_load_lds_dwordx4 v[210:211], off
	v_lshl_add_u64 v[210:211], s[20:21], 0, v[184:185]
	s_add_i32 m0, s22, 0x2000
	s_nop 0
	global_load_lds_dwordx4 v[210:211], off
	v_lshl_add_u64 v[210:211], v[222:223], 0, s[14:15]
	s_mov_b32 m0, s37
	s_nop 0
	global_load_lds_dwordx4 v[210:211], off
	v_lshl_add_u64 v[210:211], v[224:225], 0, s[14:15]
	s_mov_b32 m0, s38
	s_nop 0
	global_load_lds_dwordx4 v[210:211], off
	s_waitcnt vmcnt(8)
	s_waitcnt lgkmcnt(0)
	s_barrier
	s_setprio 1
	s_waitcnt lgkmcnt(0)
	v_mfma_f32_16x16x32_bf16 v[62:65], v[130:133], v[162:165], v[62:65]
	v_mfma_f32_16x16x32_bf16 v[58:61], v[138:141], v[162:165], v[58:61]
	v_mfma_f32_16x16x32_bf16 v[46:49], v[130:133], v[170:173], v[46:49]
	v_mfma_f32_16x16x32_bf16 v[42:45], v[138:141], v[170:173], v[42:45]
	v_mfma_f32_16x16x32_bf16 v[30:33], v[130:133], v[194:197], v[30:33]
	v_mfma_f32_16x16x32_bf16 v[26:29], v[138:141], v[194:197], v[26:29]
	v_mfma_f32_16x16x32_bf16 v[14:17], v[130:133], v[202:205], v[14:17]
	v_mfma_f32_16x16x32_bf16 v[10:13], v[138:141], v[202:205], v[10:13]
	v_mfma_f32_16x16x32_bf16 v[62:65], v[134:137], v[166:169], v[62:65]
	v_mfma_f32_16x16x32_bf16 v[58:61], v[142:145], v[166:169], v[58:61]
	v_mfma_f32_16x16x32_bf16 v[46:49], v[134:137], v[174:177], v[46:49]
	v_mfma_f32_16x16x32_bf16 v[42:45], v[142:145], v[174:177], v[42:45]
	v_mfma_f32_16x16x32_bf16 v[30:33], v[134:137], v[198:201], v[30:33]
	v_mfma_f32_16x16x32_bf16 v[26:29], v[142:145], v[198:201], v[26:29]
	v_mfma_f32_16x16x32_bf16 v[14:17], v[134:137], v[206:209], v[14:17]
	v_mfma_f32_16x16x32_bf16 v[10:13], v[142:145], v[206:209], v[10:13]
	s_setprio 0
	s_setprio 1
	v_mfma_f32_16x16x32_bf16 v[54:57], v[146:149], v[162:165], v[54:57]
	v_mfma_f32_16x16x32_bf16 v[50:53], v[154:157], v[162:165], v[50:53]
	v_mfma_f32_16x16x32_bf16 v[38:41], v[146:149], v[170:173], v[38:41]
	v_mfma_f32_16x16x32_bf16 v[34:37], v[154:157], v[170:173], v[34:37]
	v_mfma_f32_16x16x32_bf16 v[22:25], v[146:149], v[194:197], v[22:25]
	v_mfma_f32_16x16x32_bf16 v[18:21], v[154:157], v[194:197], v[18:21]
	v_mfma_f32_16x16x32_bf16 v[6:9], v[146:149], v[202:205], v[6:9]
	v_mfma_f32_16x16x32_bf16 v[2:5], v[154:157], v[202:205], v[2:5]
	v_mfma_f32_16x16x32_bf16 v[54:57], v[150:153], v[166:169], v[54:57]
	v_mfma_f32_16x16x32_bf16 v[50:53], v[158:161], v[166:169], v[50:53]
	v_mfma_f32_16x16x32_bf16 v[38:41], v[150:153], v[174:177], v[38:41]
	v_mfma_f32_16x16x32_bf16 v[34:37], v[158:161], v[174:177], v[34:37]
	v_mfma_f32_16x16x32_bf16 v[22:25], v[150:153], v[198:201], v[22:25]
	v_mfma_f32_16x16x32_bf16 v[18:21], v[158:161], v[198:201], v[18:21]
	v_mfma_f32_16x16x32_bf16 v[6:9], v[150:153], v[206:209], v[6:9]
	v_mfma_f32_16x16x32_bf16 v[2:5], v[158:161], v[206:209], v[2:5]
	s_setprio 0
	s_barrier
	s_add_i32 s51, s51, 2
	s_add_u32 s18, s18, 0x100
	s_addc_u32 s19, s19, 0
	s_add_u32 s49, s49, 0x100
	s_addc_u32 s50, s50, 0
	s_cmp_gt_u32 s51, 41
	s_cbranch_scc0 .LBB0_2471
	v_lshl_add_u32 v198, s48, 8, v1
	v_lshl_or_b32 v194, s16, 8, v212
	v_ashrrev_i32_e32 v195, 31, v194
	v_ashrrev_i32_e32 v199, 31, v198
	v_lshl_add_u64 v[196:197], v[194:195], 2, s[62:63]
	v_lshlrev_b64 v[130:131], 12, v[198:199]
	v_lshl_add_u64 v[236:237], v[196:197], 0, v[130:131]
	global_load_dwordx4 v[220:223], v[236:237], off nt
	global_load_dwordx4 v[224:227], v[236:237], off offset:16 nt
	global_load_dwordx4 v[228:231], v[236:237], off offset:512 nt
	global_load_dwordx4 v[232:235], v[236:237], off offset:528 nt
	v_or_b32_e32 v208, 16, v198
	v_or_b32_e32 v204, 32, v198
	v_or_b32_e32 v200, 48, v198
	v_ashrrev_i32_e32 v209, 31, v208
	v_ashrrev_i32_e32 v205, 31, v204
	v_ashrrev_i32_e32 v201, 31, v200
	v_lshlrev_b64 v[130:131], 12, v[208:209]
	v_lshlrev_b64 v[132:133], 12, v[204:205]
	v_lshlrev_b64 v[134:135], 12, v[200:201]
	v_lshl_add_u64 v[210:211], v[196:197], 0, v[130:131]
	v_lshl_add_u64 v[206:207], v[196:197], 0, v[132:133]
	v_lshl_add_u64 v[202:203], v[196:197], 0, v[134:135]
	global_load_dwordx4 v[170:173], v[210:211], off offset:16 nt
	global_load_dwordx4 v[174:177], v[210:211], off nt
	global_load_dwordx4 v[162:165], v[210:211], off offset:528 nt
	global_load_dwordx4 v[166:169], v[210:211], off offset:512 nt
	global_load_dwordx4 v[154:157], v[206:207], off offset:16 nt
	global_load_dwordx4 v[158:161], v[206:207], off nt
	global_load_dwordx4 v[146:149], v[206:207], off offset:528 nt
	global_load_dwordx4 v[150:153], v[206:207], off offset:512 nt
	global_load_dwordx4 v[138:141], v[202:203], off offset:16 nt
	global_load_dwordx4 v[142:145], v[202:203], off nt
	global_load_dwordx4 v[130:133], v[202:203], off offset:528 nt
	global_load_dwordx4 v[134:137], v[202:203], off offset:512 nt
	v_and_b32_e32 v238, 64, v216
	v_xor_b32_e32 v219, 16, v216
	v_add_u32_e32 v241, 64, v238
	v_cmp_lt_i32_e32 vcc, v219, v241
	v_lshlrev_b64 v[238:239], 10, v[198:199]
	v_xor_b32_e32 v240, 32, v216
	v_cndmask_b32_e32 v219, v216, v219, vcc
	v_lshlrev_b32_e32 v219, 2, v219
	v_lshl_add_u64 v[238:239], v[238:239], 0, v[194:195]
	v_cmp_lt_i32_e32 vcc, v240, v241
	v_lshlrev_b64 v[238:239], 1, v[238:239]
	s_lshl_b32 s18, s16, 2
	v_cndmask_b32_e32 v242, v216, v240, vcc
	v_lshl_add_u64 v[240:241], s[2:3], 0, v[238:239]
	v_or_b32_e32 v238, 0x100, v238
	s_ashr_i32 s19, s18, 31
	s_waitcnt vmcnt(0)
	v_pk_fma_f32 v[128:129], v[128:129], 0.5, v[222:223] op_sel_hi:[1,0,1]
	v_pk_fma_f32 v[126:127], v[126:127], 0.5, v[220:221] op_sel_hi:[1,0,1]
	v_pk_fma_f32 v[120:121], v[120:121], 0.5, v[230:231] op_sel_hi:[1,0,1]
	v_pk_fma_f32 v[118:119], v[118:119], 0.5, v[228:229] op_sel_hi:[1,0,1]
	v_pk_fma_f32 v[124:125], v[124:125], 0.5, v[226:227] op_sel_hi:[1,0,1]
	v_pk_fma_f32 v[122:123], v[122:123], 0.5, v[224:225] op_sel_hi:[1,0,1]
	v_pk_fma_f32 v[114:115], v[114:115], 0.5, v[232:233] op_sel_hi:[1,0,1]
	global_store_dwordx4 v[236:237], v[126:129], off nt
	global_store_dwordx4 v[236:237], v[122:125], off offset:16 nt
	v_cvt_pk_bf16_f32 v220, v126, v127
	v_cvt_pk_bf16_f32 v221, v128, v129
	v_mul_f32_e32 v224, v119, v119
	v_mul_f32_e32 v127, v127, v127
	v_mul_f32_e32 v129, v129, v129
	v_mul_f32_e32 v225, v121, v121
	v_pk_fma_f32 v[116:117], v[116:117], 0.5, v[234:235] op_sel_hi:[1,0,1]
	v_cvt_pk_bf16_f32 v222, v122, v123
	v_cvt_pk_bf16_f32 v223, v124, v125
	v_mul_f32_e32 v123, v123, v123
	v_mul_f32_e32 v125, v125, v125
	v_mul_f32_e32 v226, v115, v115
	v_fmac_f32_e32 v127, v126, v126
	v_fmac_f32_e32 v129, v128, v128
	v_fmac_f32_e32 v224, v118, v118
	v_fmac_f32_e32 v225, v120, v120
	v_mul_f32_e32 v227, v117, v117
	v_fmac_f32_e32 v123, v122, v122
	v_fmac_f32_e32 v125, v124, v124
	v_fmac_f32_e32 v226, v114, v114
	v_add_f32_e32 v122, v127, v129
	v_add_f32_e32 v124, v224, v225
	v_fmac_f32_e32 v227, v116, v116
	v_add_f32_e32 v122, v122, v123
	v_add_f32_e32 v123, v124, v226
	v_add_f32_e32 v122, v125, v122
	v_add_f32_e32 v123, v227, v123
	v_add_f32_e32 v122, v122, v123
	ds_bpermute_b32 v123, v219, v122
	global_store_dwordx4 v[240:241], v[220:223], off nt
	global_store_dwordx4 v[236:237], v[118:121], off offset:512 nt
	global_store_dwordx4 v[236:237], v[114:117], off offset:528 nt
	v_lshlrev_b32_e32 v128, 2, v242
	v_cvt_pk_bf16_f32 v118, v118, v119
	v_cvt_pk_bf16_f32 v119, v120, v121
	v_cvt_pk_bf16_f32 v120, v114, v115
	v_cvt_pk_bf16_f32 v121, v116, v117
	s_waitcnt lgkmcnt(0)
	v_add_f32_e32 v114, v122, v123
	ds_bpermute_b32 v115, v128, v114
	v_lshl_add_u64 v[116:117], s[2:3], 0, v[238:239]
	global_store_dwordx4 v[116:117], v[118:121], off nt
	s_and_saveexec_b64 s[20:21], s[4:5]
	s_cbranch_execz .LBB0_2474
	s_waitcnt lgkmcnt(0)
	v_add_f32_e32 v116, v114, v115
	v_lshlrev_b64 v[114:115], 6, v[198:199]
	v_lshl_add_u64 v[114:115], s[12:13], 0, v[114:115]
	v_lshl_add_u64 v[114:115], s[18:19], 2, v[114:115]
	s_lshl_b32 s16, s36, 2
	v_lshl_add_u64 v[114:115], v[114:115], 0, s[16:17]
	global_store_dword v[114:115], v116, off
.LBB0_2474:
	s_or_b64 exec, exec, s[20:21]
	s_waitcnt lgkmcnt(0)
	v_lshlrev_b64 v[114:115], 10, v[208:209]
	v_pk_fma_f32 v[112:113], v[112:113], 0.5, v[176:177] op_sel_hi:[1,0,1]
	v_pk_fma_f32 v[110:111], v[110:111], 0.5, v[174:175] op_sel_hi:[1,0,1]
	v_lshl_add_u64 v[118:119], v[114:115], 0, v[194:195]
	v_pk_fma_f32 v[108:109], v[108:109], 0.5, v[172:173] op_sel_hi:[1,0,1]
	v_pk_fma_f32 v[106:107], v[106:107], 0.5, v[170:171] op_sel_hi:[1,0,1]
	global_store_dwordx4 v[210:211], v[110:113], off nt
	global_store_dwordx4 v[210:211], v[106:109], off offset:16 nt
	v_cvt_pk_bf16_f32 v114, v110, v111
	v_cvt_pk_bf16_f32 v115, v112, v113
	v_cvt_pk_bf16_f32 v116, v106, v107
	v_pk_fma_f32 v[104:105], v[104:105], 0.5, v[168:169] op_sel_hi:[1,0,1]
	v_mul_f32_e32 v111, v111, v111
	v_fmac_f32_e32 v111, v110, v110
	v_mul_f32_e32 v110, v113, v113
	v_fmac_f32_e32 v110, v112, v112
	v_mul_f32_e32 v107, v107, v107
	v_add_f32_e32 v110, v111, v110
	v_fmac_f32_e32 v107, v106, v106
	v_add_f32_e32 v106, v110, v107
	v_mul_f32_e32 v107, v109, v109
	v_fmac_f32_e32 v107, v108, v108
	v_pk_fma_f32 v[102:103], v[102:103], 0.5, v[166:167] op_sel_hi:[1,0,1]
	v_cvt_pk_bf16_f32 v117, v108, v109
	v_add_f32_e32 v106, v107, v106
	v_mul_f32_e32 v107, v103, v103
	v_mul_f32_e32 v108, v105, v105
	v_pk_fma_f32 v[98:99], v[98:99], 0.5, v[162:163] op_sel_hi:[1,0,1]
	v_fmac_f32_e32 v107, v102, v102
	v_fmac_f32_e32 v108, v104, v104
	v_add_f32_e32 v107, v107, v108
	v_mul_f32_e32 v108, v99, v99
	v_pk_fma_f32 v[100:101], v[100:101], 0.5, v[164:165] op_sel_hi:[1,0,1]
	v_fmac_f32_e32 v108, v98, v98
	v_add_f32_e32 v107, v107, v108
	v_mul_f32_e32 v108, v101, v101
	v_fmac_f32_e32 v108, v100, v100
	v_add_f32_e32 v107, v108, v107
	v_add_f32_e32 v106, v106, v107
	ds_bpermute_b32 v107, v219, v106
	v_lshlrev_b64 v[118:119], 1, v[118:119]
	v_lshl_add_u64 v[120:121], s[2:3], 0, v[118:119]
	global_store_dwordx4 v[120:121], v[114:117], off nt
	global_store_dwordx4 v[210:211], v[102:105], off offset:512 nt
	global_store_dwordx4 v[210:211], v[98:101], off offset:528 nt
	v_or_b32_e32 v118, 0x100, v118
	v_cvt_pk_bf16_f32 v102, v102, v103
	v_cvt_pk_bf16_f32 v103, v104, v105
	v_cvt_pk_bf16_f32 v104, v98, v99
	v_cvt_pk_bf16_f32 v105, v100, v101
	s_waitcnt lgkmcnt(0)
	v_add_f32_e32 v98, v106, v107
	ds_bpermute_b32 v99, v128, v98
	v_lshl_add_u64 v[100:101], s[2:3], 0, v[118:119]
	global_store_dwordx4 v[100:101], v[102:105], off nt
	s_and_saveexec_b64 s[20:21], s[4:5]
	s_cbranch_execz .LBB0_2476
	s_waitcnt lgkmcnt(0)
	v_add_f32_e32 v100, v98, v99
	v_lshlrev_b64 v[98:99], 6, v[208:209]
	v_lshl_add_u64 v[98:99], s[12:13], 0, v[98:99]
	v_lshl_add_u64 v[98:99], s[18:19], 2, v[98:99]
	s_lshl_b32 s16, s36, 2
	v_lshl_add_u64 v[98:99], v[98:99], 0, s[16:17]
	global_store_dword v[98:99], v100, off
.LBB0_2476:
	s_or_b64 exec, exec, s[20:21]
	s_waitcnt lgkmcnt(0)
	v_lshlrev_b64 v[98:99], 10, v[204:205]
	v_pk_fma_f32 v[96:97], v[96:97], 0.5, v[160:161] op_sel_hi:[1,0,1]
	v_pk_fma_f32 v[94:95], v[94:95], 0.5, v[158:159] op_sel_hi:[1,0,1]
	v_lshl_add_u64 v[102:103], v[98:99], 0, v[194:195]
	v_pk_fma_f32 v[92:93], v[92:93], 0.5, v[156:157] op_sel_hi:[1,0,1]
	v_pk_fma_f32 v[90:91], v[90:91], 0.5, v[154:155] op_sel_hi:[1,0,1]
	global_store_dwordx4 v[206:207], v[94:97], off nt
	global_store_dwordx4 v[206:207], v[90:93], off offset:16 nt
	v_cvt_pk_bf16_f32 v98, v94, v95
	v_cvt_pk_bf16_f32 v99, v96, v97
	v_cvt_pk_bf16_f32 v100, v90, v91
	v_pk_fma_f32 v[88:89], v[88:89], 0.5, v[152:153] op_sel_hi:[1,0,1]
	v_mul_f32_e32 v95, v95, v95
	v_fmac_f32_e32 v95, v94, v94
	v_mul_f32_e32 v94, v97, v97
	v_fmac_f32_e32 v94, v96, v96
	v_mul_f32_e32 v91, v91, v91
	v_add_f32_e32 v94, v95, v94
	v_fmac_f32_e32 v91, v90, v90
	v_add_f32_e32 v90, v94, v91
	v_mul_f32_e32 v91, v93, v93
	v_fmac_f32_e32 v91, v92, v92
	v_pk_fma_f32 v[86:87], v[86:87], 0.5, v[150:151] op_sel_hi:[1,0,1]
	v_cvt_pk_bf16_f32 v101, v92, v93
	v_add_f32_e32 v90, v91, v90
	v_mul_f32_e32 v91, v87, v87
	v_mul_f32_e32 v92, v89, v89
	v_pk_fma_f32 v[82:83], v[82:83], 0.5, v[146:147] op_sel_hi:[1,0,1]
	v_fmac_f32_e32 v91, v86, v86
	v_fmac_f32_e32 v92, v88, v88
	v_add_f32_e32 v91, v91, v92
	v_mul_f32_e32 v92, v83, v83
	v_pk_fma_f32 v[84:85], v[84:85], 0.5, v[148:149] op_sel_hi:[1,0,1]
	v_fmac_f32_e32 v92, v82, v82
	v_add_f32_e32 v91, v91, v92
	v_mul_f32_e32 v92, v85, v85
	v_fmac_f32_e32 v92, v84, v84
	v_add_f32_e32 v91, v92, v91
	v_add_f32_e32 v90, v90, v91
	ds_bpermute_b32 v91, v219, v90
	v_lshlrev_b64 v[102:103], 1, v[102:103]
	v_lshl_add_u64 v[104:105], s[2:3], 0, v[102:103]
	global_store_dwordx4 v[104:105], v[98:101], off nt
	global_store_dwordx4 v[206:207], v[86:89], off offset:512 nt
	global_store_dwordx4 v[206:207], v[82:85], off offset:528 nt
	v_or_b32_e32 v102, 0x100, v102
	v_cvt_pk_bf16_f32 v86, v86, v87
	v_cvt_pk_bf16_f32 v87, v88, v89
	v_cvt_pk_bf16_f32 v88, v82, v83
	v_cvt_pk_bf16_f32 v89, v84, v85
	s_waitcnt lgkmcnt(0)
	v_add_f32_e32 v82, v90, v91
	ds_bpermute_b32 v83, v128, v82
	v_lshl_add_u64 v[84:85], s[2:3], 0, v[102:103]
	global_store_dwordx4 v[84:85], v[86:89], off nt
	s_and_saveexec_b64 s[20:21], s[4:5]
	s_cbranch_execz .LBB0_2478
	s_waitcnt lgkmcnt(0)
	v_add_f32_e32 v84, v82, v83
	v_lshlrev_b64 v[82:83], 6, v[204:205]
	v_lshl_add_u64 v[82:83], s[12:13], 0, v[82:83]
	v_lshl_add_u64 v[82:83], s[18:19], 2, v[82:83]
	s_lshl_b32 s16, s36, 2
	v_lshl_add_u64 v[82:83], v[82:83], 0, s[16:17]
	global_store_dword v[82:83], v84, off
.LBB0_2478:
	s_or_b64 exec, exec, s[20:21]
	s_waitcnt lgkmcnt(0)
	v_lshlrev_b64 v[82:83], 10, v[200:201]
	v_pk_fma_f32 v[80:81], v[80:81], 0.5, v[144:145] op_sel_hi:[1,0,1]
	v_pk_fma_f32 v[78:79], v[78:79], 0.5, v[142:143] op_sel_hi:[1,0,1]
	v_lshl_add_u64 v[86:87], v[82:83], 0, v[194:195]
	v_pk_fma_f32 v[76:77], v[76:77], 0.5, v[140:141] op_sel_hi:[1,0,1]
	v_pk_fma_f32 v[74:75], v[74:75], 0.5, v[138:139] op_sel_hi:[1,0,1]
	global_store_dwordx4 v[202:203], v[78:81], off nt
	global_store_dwordx4 v[202:203], v[74:77], off offset:16 nt
	v_cvt_pk_bf16_f32 v82, v78, v79
	v_cvt_pk_bf16_f32 v83, v80, v81
	v_cvt_pk_bf16_f32 v84, v74, v75
	v_pk_fma_f32 v[72:73], v[72:73], 0.5, v[136:137] op_sel_hi:[1,0,1]
	v_mul_f32_e32 v79, v79, v79
	v_fmac_f32_e32 v79, v78, v78
	v_mul_f32_e32 v78, v81, v81
	v_fmac_f32_e32 v78, v80, v80
	v_mul_f32_e32 v75, v75, v75
	v_add_f32_e32 v78, v79, v78
	v_fmac_f32_e32 v75, v74, v74
	v_add_f32_e32 v74, v78, v75
	v_mul_f32_e32 v75, v77, v77
	v_fmac_f32_e32 v75, v76, v76
	v_pk_fma_f32 v[70:71], v[70:71], 0.5, v[134:135] op_sel_hi:[1,0,1]
	v_cvt_pk_bf16_f32 v85, v76, v77
	v_add_f32_e32 v74, v75, v74
	v_mul_f32_e32 v75, v71, v71
	v_mul_f32_e32 v76, v73, v73
	v_pk_fma_f32 v[66:67], v[66:67], 0.5, v[130:131] op_sel_hi:[1,0,1]
	v_fmac_f32_e32 v75, v70, v70
	v_fmac_f32_e32 v76, v72, v72
	v_add_f32_e32 v75, v75, v76
	v_mul_f32_e32 v76, v67, v67
	v_pk_fma_f32 v[68:69], v[68:69], 0.5, v[132:133] op_sel_hi:[1,0,1]
	v_fmac_f32_e32 v76, v66, v66
	v_add_f32_e32 v75, v75, v76
	v_mul_f32_e32 v76, v69, v69
	v_fmac_f32_e32 v76, v68, v68
	v_add_f32_e32 v75, v76, v75
	v_add_f32_e32 v74, v74, v75
	ds_bpermute_b32 v75, v219, v74
	v_lshlrev_b64 v[86:87], 1, v[86:87]
	v_lshl_add_u64 v[88:89], s[2:3], 0, v[86:87]
	global_store_dwordx4 v[88:89], v[82:85], off nt
	global_store_dwordx4 v[202:203], v[70:73], off offset:512 nt
	global_store_dwordx4 v[202:203], v[66:69], off offset:528 nt
	v_or_b32_e32 v86, 0x100, v86
	v_cvt_pk_bf16_f32 v70, v70, v71
	v_cvt_pk_bf16_f32 v71, v72, v73
	v_cvt_pk_bf16_f32 v72, v66, v67
	v_cvt_pk_bf16_f32 v73, v68, v69
	s_waitcnt lgkmcnt(0)
	v_add_f32_e32 v66, v74, v75
	ds_bpermute_b32 v67, v128, v66
	v_lshl_add_u64 v[68:69], s[2:3], 0, v[86:87]
	global_store_dwordx4 v[68:69], v[70:73], off nt
	s_and_saveexec_b64 s[20:21], s[4:5]
	s_cbranch_execz .LBB0_2480
	s_waitcnt lgkmcnt(0)
	v_add_f32_e32 v68, v66, v67
	v_lshlrev_b64 v[66:67], 6, v[200:201]
	v_lshl_add_u64 v[66:67], s[12:13], 0, v[66:67]
	v_lshl_add_u64 v[66:67], s[18:19], 2, v[66:67]
	s_lshl_b32 s16, s36, 2
	v_lshl_add_u64 v[66:67], v[66:67], 0, s[16:17]
	global_store_dword v[66:67], v68, off
.LBB0_2480:
	s_or_b64 exec, exec, s[20:21]
	v_add_u32_e32 v126, 0x80, v198
	v_ashrrev_i32_e32 v127, 31, v126
	s_waitcnt lgkmcnt(0)
	v_lshlrev_b64 v[66:67], 12, v[126:127]
	v_lshl_add_u64 v[146:147], v[196:197], 0, v[66:67]
	global_load_dwordx4 v[130:133], v[146:147], off nt
	global_load_dwordx4 v[134:137], v[146:147], off offset:16 nt
	global_load_dwordx4 v[138:141], v[146:147], off offset:512 nt
	global_load_dwordx4 v[142:145], v[146:147], off offset:528 nt
	v_add_u32_e32 v122, 0x90, v198
	v_add_u32_e32 v118, 0xa0, v198
	v_add_u32_e32 v114, 0xb0, v198
	v_ashrrev_i32_e32 v123, 31, v122
	v_ashrrev_i32_e32 v119, 31, v118
	v_ashrrev_i32_e32 v115, 31, v114
	v_lshlrev_b64 v[66:67], 12, v[122:123]
	v_lshlrev_b64 v[68:69], 12, v[118:119]
	v_lshlrev_b64 v[70:71], 12, v[114:115]
	v_lshl_add_u64 v[124:125], v[196:197], 0, v[66:67]
	v_lshl_add_u64 v[120:121], v[196:197], 0, v[68:69]
	v_lshl_add_u64 v[116:117], v[196:197], 0, v[70:71]
	global_load_dwordx4 v[106:109], v[124:125], off offset:16 nt
	global_load_dwordx4 v[110:113], v[124:125], off nt
	global_load_dwordx4 v[98:101], v[124:125], off offset:528 nt
	global_load_dwordx4 v[102:105], v[124:125], off offset:512 nt
	global_load_dwordx4 v[90:93], v[120:121], off offset:16 nt
	global_load_dwordx4 v[94:97], v[120:121], off nt
	global_load_dwordx4 v[82:85], v[120:121], off offset:528 nt
	global_load_dwordx4 v[86:89], v[120:121], off offset:512 nt
	global_load_dwordx4 v[74:77], v[116:117], off offset:16 nt
	global_load_dwordx4 v[78:81], v[116:117], off nt
	global_load_dwordx4 v[66:69], v[116:117], off offset:528 nt
	global_load_dwordx4 v[70:73], v[116:117], off offset:512 nt
	v_lshlrev_b64 v[148:149], 10, v[126:127]
	v_lshl_add_u64 v[148:149], v[148:149], 0, v[194:195]
	v_lshlrev_b64 v[148:149], 1, v[148:149]
	v_lshl_add_u64 v[150:151], s[2:3], 0, v[148:149]
	v_or_b32_e32 v148, 0x100, v148
	s_waitcnt vmcnt(15)
	v_pk_fma_f32 v[64:65], v[64:65], 0.5, v[132:133] op_sel_hi:[1,0,1]
	v_pk_fma_f32 v[62:63], v[62:63], 0.5, v[130:131] op_sel_hi:[1,0,1]
	s_waitcnt vmcnt(13)
	v_pk_fma_f32 v[56:57], v[56:57], 0.5, v[140:141] op_sel_hi:[1,0,1]
	v_pk_fma_f32 v[54:55], v[54:55], 0.5, v[138:139] op_sel_hi:[1,0,1]
	v_pk_fma_f32 v[60:61], v[60:61], 0.5, v[136:137] op_sel_hi:[1,0,1]
	v_pk_fma_f32 v[58:59], v[58:59], 0.5, v[134:135] op_sel_hi:[1,0,1]
	s_waitcnt vmcnt(12)
	v_pk_fma_f32 v[50:51], v[50:51], 0.5, v[142:143] op_sel_hi:[1,0,1]
	global_store_dwordx4 v[146:147], v[62:65], off nt
	global_store_dwordx4 v[146:147], v[58:61], off offset:16 nt
	v_cvt_pk_bf16_f32 v130, v62, v63
	v_cvt_pk_bf16_f32 v131, v64, v65
	v_mul_f32_e32 v129, v55, v55
	v_mul_f32_e32 v63, v63, v63
	v_mul_f32_e32 v65, v65, v65
	v_mul_f32_e32 v134, v57, v57
	v_pk_fma_f32 v[52:53], v[52:53], 0.5, v[144:145] op_sel_hi:[1,0,1]
	v_cvt_pk_bf16_f32 v132, v58, v59
	v_cvt_pk_bf16_f32 v133, v60, v61
	v_mul_f32_e32 v59, v59, v59
	v_mul_f32_e32 v61, v61, v61
	v_mul_f32_e32 v135, v51, v51
	v_fmac_f32_e32 v63, v62, v62
	v_fmac_f32_e32 v65, v64, v64
	v_fmac_f32_e32 v129, v54, v54
	v_fmac_f32_e32 v134, v56, v56
	v_mul_f32_e32 v136, v53, v53
	v_fmac_f32_e32 v59, v58, v58
	v_fmac_f32_e32 v61, v60, v60
	v_fmac_f32_e32 v135, v50, v50
	v_add_f32_e32 v58, v63, v65
	v_add_f32_e32 v60, v129, v134
	v_fmac_f32_e32 v136, v52, v52
	v_add_f32_e32 v58, v58, v59
	v_add_f32_e32 v59, v60, v135
	v_add_f32_e32 v58, v61, v58
	v_add_f32_e32 v59, v136, v59
	v_add_f32_e32 v58, v58, v59
	ds_bpermute_b32 v59, v219, v58
	global_store_dwordx4 v[150:151], v[130:133], off nt
	global_store_dwordx4 v[146:147], v[54:57], off offset:512 nt
	global_store_dwordx4 v[146:147], v[50:53], off offset:528 nt
	s_nop 0
	v_cvt_pk_bf16_f32 v54, v54, v55
	v_cvt_pk_bf16_f32 v55, v56, v57
	v_cvt_pk_bf16_f32 v56, v50, v51
	v_cvt_pk_bf16_f32 v57, v52, v53
	s_waitcnt lgkmcnt(0)
	v_add_f32_e32 v50, v58, v59
	ds_bpermute_b32 v51, v128, v50
	v_lshl_add_u64 v[52:53], s[2:3], 0, v[148:149]
	global_store_dwordx4 v[52:53], v[54:57], off nt
	s_and_saveexec_b64 s[20:21], s[4:5]
	s_cbranch_execz .LBB0_2482
	s_waitcnt lgkmcnt(0)
	v_add_f32_e32 v52, v50, v51
	v_lshlrev_b64 v[50:51], 6, v[126:127]
	v_lshl_add_u64 v[50:51], s[12:13], 0, v[50:51]
	v_lshl_add_u64 v[50:51], s[18:19], 2, v[50:51]
	s_lshl_b32 s16, s36, 2
	v_lshl_add_u64 v[50:51], v[50:51], 0, s[16:17]
	global_store_dword v[50:51], v52, off
.LBB0_2482:
	s_or_b64 exec, exec, s[20:21]
	s_waitcnt lgkmcnt(0)
	v_lshlrev_b64 v[50:51], 10, v[122:123]
	s_waitcnt vmcnt(16)
	v_pk_fma_f32 v[48:49], v[48:49], 0.5, v[112:113] op_sel_hi:[1,0,1]
	v_pk_fma_f32 v[46:47], v[46:47], 0.5, v[110:111] op_sel_hi:[1,0,1]
	v_lshl_add_u64 v[54:55], v[50:51], 0, v[194:195]
	v_pk_fma_f32 v[44:45], v[44:45], 0.5, v[108:109] op_sel_hi:[1,0,1]
	v_pk_fma_f32 v[42:43], v[42:43], 0.5, v[106:107] op_sel_hi:[1,0,1]
	global_store_dwordx4 v[124:125], v[46:49], off nt
	global_store_dwordx4 v[124:125], v[42:45], off offset:16 nt
	v_cvt_pk_bf16_f32 v50, v46, v47
	v_cvt_pk_bf16_f32 v51, v48, v49
	v_cvt_pk_bf16_f32 v52, v42, v43
	s_waitcnt vmcnt(16)
	v_pk_fma_f32 v[40:41], v[40:41], 0.5, v[104:105] op_sel_hi:[1,0,1]
	v_mul_f32_e32 v47, v47, v47
	v_fmac_f32_e32 v47, v46, v46
	v_mul_f32_e32 v46, v49, v49
	v_fmac_f32_e32 v46, v48, v48
	v_mul_f32_e32 v43, v43, v43
	v_add_f32_e32 v46, v47, v46
	v_fmac_f32_e32 v43, v42, v42
	v_add_f32_e32 v42, v46, v43
	v_mul_f32_e32 v43, v45, v45
	v_fmac_f32_e32 v43, v44, v44
	v_pk_fma_f32 v[38:39], v[38:39], 0.5, v[102:103] op_sel_hi:[1,0,1]
	v_cvt_pk_bf16_f32 v53, v44, v45
	v_add_f32_e32 v42, v43, v42
	v_mul_f32_e32 v43, v39, v39
	v_mul_f32_e32 v44, v41, v41
	v_pk_fma_f32 v[34:35], v[34:35], 0.5, v[98:99] op_sel_hi:[1,0,1]
	v_fmac_f32_e32 v43, v38, v38
	v_fmac_f32_e32 v44, v40, v40
	v_add_f32_e32 v43, v43, v44
	v_mul_f32_e32 v44, v35, v35
	v_pk_fma_f32 v[36:37], v[36:37], 0.5, v[100:101] op_sel_hi:[1,0,1]
	v_fmac_f32_e32 v44, v34, v34
	v_add_f32_e32 v43, v43, v44
	v_mul_f32_e32 v44, v37, v37
	v_fmac_f32_e32 v44, v36, v36
	v_add_f32_e32 v43, v44, v43
	v_add_f32_e32 v42, v42, v43
	ds_bpermute_b32 v43, v219, v42
	v_lshlrev_b64 v[54:55], 1, v[54:55]
	v_lshl_add_u64 v[56:57], s[2:3], 0, v[54:55]
	global_store_dwordx4 v[56:57], v[50:53], off nt
	global_store_dwordx4 v[124:125], v[38:41], off offset:512 nt
	global_store_dwordx4 v[124:125], v[34:37], off offset:528 nt
	v_or_b32_e32 v54, 0x100, v54
	v_cvt_pk_bf16_f32 v38, v38, v39
	v_cvt_pk_bf16_f32 v39, v40, v41
	v_cvt_pk_bf16_f32 v40, v34, v35
	v_cvt_pk_bf16_f32 v41, v36, v37
	s_waitcnt lgkmcnt(0)
	v_add_f32_e32 v34, v42, v43
	ds_bpermute_b32 v35, v128, v34
	v_lshl_add_u64 v[36:37], s[2:3], 0, v[54:55]
	global_store_dwordx4 v[36:37], v[38:41], off nt
	s_and_saveexec_b64 s[20:21], s[4:5]
	s_cbranch_execz .LBB0_2484
	s_waitcnt lgkmcnt(0)
	v_add_f32_e32 v36, v34, v35
	v_lshlrev_b64 v[34:35], 6, v[122:123]
	v_lshl_add_u64 v[34:35], s[12:13], 0, v[34:35]
	v_lshl_add_u64 v[34:35], s[18:19], 2, v[34:35]
	s_lshl_b32 s16, s36, 2
	v_lshl_add_u64 v[34:35], v[34:35], 0, s[16:17]
	global_store_dword v[34:35], v36, off
.LBB0_2484:
	s_or_b64 exec, exec, s[20:21]
	s_waitcnt lgkmcnt(0)
	v_lshlrev_b64 v[34:35], 10, v[118:119]
	s_waitcnt vmcnt(18)
	v_pk_fma_f32 v[32:33], v[32:33], 0.5, v[96:97] op_sel_hi:[1,0,1]
	v_pk_fma_f32 v[30:31], v[30:31], 0.5, v[94:95] op_sel_hi:[1,0,1]
	v_lshl_add_u64 v[38:39], v[34:35], 0, v[194:195]
	v_pk_fma_f32 v[28:29], v[28:29], 0.5, v[92:93] op_sel_hi:[1,0,1]
	v_pk_fma_f32 v[26:27], v[26:27], 0.5, v[90:91] op_sel_hi:[1,0,1]
	global_store_dwordx4 v[120:121], v[30:33], off nt
	global_store_dwordx4 v[120:121], v[26:29], off offset:16 nt
	v_cvt_pk_bf16_f32 v34, v30, v31
	v_cvt_pk_bf16_f32 v35, v32, v33
	v_cvt_pk_bf16_f32 v36, v26, v27
	s_waitcnt vmcnt(18)
	v_pk_fma_f32 v[24:25], v[24:25], 0.5, v[88:89] op_sel_hi:[1,0,1]
	v_mul_f32_e32 v31, v31, v31
	v_fmac_f32_e32 v31, v30, v30
	v_mul_f32_e32 v30, v33, v33
	v_fmac_f32_e32 v30, v32, v32
	v_mul_f32_e32 v27, v27, v27
	v_add_f32_e32 v30, v31, v30
	v_fmac_f32_e32 v27, v26, v26
	v_add_f32_e32 v26, v30, v27
	v_mul_f32_e32 v27, v29, v29
	v_fmac_f32_e32 v27, v28, v28
	v_pk_fma_f32 v[22:23], v[22:23], 0.5, v[86:87] op_sel_hi:[1,0,1]
	v_cvt_pk_bf16_f32 v37, v28, v29
	v_add_f32_e32 v26, v27, v26
	v_mul_f32_e32 v27, v23, v23
	v_mul_f32_e32 v28, v25, v25
	v_pk_fma_f32 v[18:19], v[18:19], 0.5, v[82:83] op_sel_hi:[1,0,1]
	v_fmac_f32_e32 v27, v22, v22
	v_fmac_f32_e32 v28, v24, v24
	v_add_f32_e32 v27, v27, v28
	v_mul_f32_e32 v28, v19, v19
	v_pk_fma_f32 v[20:21], v[20:21], 0.5, v[84:85] op_sel_hi:[1,0,1]
	v_fmac_f32_e32 v28, v18, v18
	v_add_f32_e32 v27, v27, v28
	v_mul_f32_e32 v28, v21, v21
	v_fmac_f32_e32 v28, v20, v20
	v_add_f32_e32 v27, v28, v27
	v_add_f32_e32 v26, v26, v27
	ds_bpermute_b32 v27, v219, v26
	v_lshlrev_b64 v[38:39], 1, v[38:39]
	v_lshl_add_u64 v[40:41], s[2:3], 0, v[38:39]
	global_store_dwordx4 v[40:41], v[34:37], off nt
	global_store_dwordx4 v[120:121], v[22:25], off offset:512 nt
	global_store_dwordx4 v[120:121], v[18:21], off offset:528 nt
	v_or_b32_e32 v38, 0x100, v38
	v_cvt_pk_bf16_f32 v22, v22, v23
	v_cvt_pk_bf16_f32 v23, v24, v25
	v_cvt_pk_bf16_f32 v24, v18, v19
	v_cvt_pk_bf16_f32 v25, v20, v21
	s_waitcnt lgkmcnt(0)
	v_add_f32_e32 v18, v26, v27
	ds_bpermute_b32 v19, v128, v18
	v_lshl_add_u64 v[20:21], s[2:3], 0, v[38:39]
	global_store_dwordx4 v[20:21], v[22:25], off nt
	s_and_saveexec_b64 s[20:21], s[4:5]
	s_cbranch_execz .LBB0_2486
	s_waitcnt lgkmcnt(0)
	v_add_f32_e32 v20, v18, v19
	v_lshlrev_b64 v[18:19], 6, v[118:119]
	v_lshl_add_u64 v[18:19], s[12:13], 0, v[18:19]
	v_lshl_add_u64 v[18:19], s[18:19], 2, v[18:19]
	s_lshl_b32 s16, s36, 2
	v_lshl_add_u64 v[18:19], v[18:19], 0, s[16:17]
	global_store_dword v[18:19], v20, off
.LBB0_2486:
	s_or_b64 exec, exec, s[20:21]
	s_waitcnt lgkmcnt(0)
	v_lshlrev_b64 v[18:19], 10, v[114:115]
	s_waitcnt vmcnt(20)
	v_pk_fma_f32 v[16:17], v[16:17], 0.5, v[80:81] op_sel_hi:[1,0,1]
	v_pk_fma_f32 v[14:15], v[14:15], 0.5, v[78:79] op_sel_hi:[1,0,1]
	v_lshl_add_u64 v[22:23], v[18:19], 0, v[194:195]
	v_pk_fma_f32 v[12:13], v[12:13], 0.5, v[76:77] op_sel_hi:[1,0,1]
	v_pk_fma_f32 v[10:11], v[10:11], 0.5, v[74:75] op_sel_hi:[1,0,1]
	global_store_dwordx4 v[116:117], v[14:17], off nt
	global_store_dwordx4 v[116:117], v[10:13], off offset:16 nt
	v_cvt_pk_bf16_f32 v18, v14, v15
	v_cvt_pk_bf16_f32 v19, v16, v17
	v_cvt_pk_bf16_f32 v20, v10, v11
	s_waitcnt vmcnt(20)
	v_pk_fma_f32 v[8:9], v[8:9], 0.5, v[72:73] op_sel_hi:[1,0,1]
	v_mul_f32_e32 v15, v15, v15
	v_fmac_f32_e32 v15, v14, v14
	v_mul_f32_e32 v14, v17, v17
	v_fmac_f32_e32 v14, v16, v16
	v_mul_f32_e32 v11, v11, v11
	v_add_f32_e32 v14, v15, v14
	v_fmac_f32_e32 v11, v10, v10
	v_add_f32_e32 v10, v14, v11
	v_mul_f32_e32 v11, v13, v13
	v_fmac_f32_e32 v11, v12, v12
	v_pk_fma_f32 v[6:7], v[6:7], 0.5, v[70:71] op_sel_hi:[1,0,1]
	v_cvt_pk_bf16_f32 v21, v12, v13
	v_add_f32_e32 v10, v11, v10
	v_mul_f32_e32 v11, v7, v7
	v_mul_f32_e32 v12, v9, v9
	v_pk_fma_f32 v[2:3], v[2:3], 0.5, v[66:67] op_sel_hi:[1,0,1]
	v_fmac_f32_e32 v11, v6, v6
	v_fmac_f32_e32 v12, v8, v8
	v_add_f32_e32 v11, v11, v12
	v_mul_f32_e32 v12, v3, v3
	v_pk_fma_f32 v[4:5], v[4:5], 0.5, v[68:69] op_sel_hi:[1,0,1]
	v_fmac_f32_e32 v12, v2, v2
	v_add_f32_e32 v11, v11, v12
	v_mul_f32_e32 v12, v5, v5
	v_fmac_f32_e32 v12, v4, v4
	v_add_f32_e32 v11, v12, v11
	v_add_f32_e32 v10, v10, v11
	ds_bpermute_b32 v11, v219, v10
	v_lshlrev_b64 v[22:23], 1, v[22:23]
	v_lshl_add_u64 v[24:25], s[2:3], 0, v[22:23]
	global_store_dwordx4 v[24:25], v[18:21], off nt
	global_store_dwordx4 v[116:117], v[6:9], off offset:512 nt
	global_store_dwordx4 v[116:117], v[2:5], off offset:528 nt
	v_or_b32_e32 v22, 0x100, v22
	v_cvt_pk_bf16_f32 v6, v6, v7
	v_cvt_pk_bf16_f32 v7, v8, v9
	v_cvt_pk_bf16_f32 v8, v2, v3
	v_cvt_pk_bf16_f32 v9, v4, v5
	s_waitcnt lgkmcnt(0)
	v_add_f32_e32 v2, v10, v11
	ds_bpermute_b32 v3, v128, v2
	v_lshl_add_u64 v[4:5], s[2:3], 0, v[22:23]
	global_store_dwordx4 v[4:5], v[6:9], off nt
	s_and_saveexec_b64 s[20:21], s[4:5]
	s_cbranch_execz .LBB0_2459
	s_waitcnt lgkmcnt(0)
	v_add_f32_e32 v4, v2, v3
	v_lshlrev_b64 v[2:3], 6, v[114:115]
	v_lshl_add_u64 v[2:3], s[12:13], 0, v[2:3]
	v_lshl_add_u64 v[2:3], s[18:19], 2, v[2:3]
	s_lshl_b32 s16, s36, 2
	v_lshl_add_u64 v[2:3], v[2:3], 0, s[16:17]
	global_store_dword v[2:3], v4, off
	s_branch .LBB0_2459
